# GEMM phases: one combined wait before each phase barrier, no repeated lgkm wait behind it, no priority drop between the two MFMA blocks
# baseline (speedup 1.0000x reference)
.LBB0_153:
	ds_read_b128 v[138:141], v170
	ds_read_b128 v[152:155], v170 offset:1024
	ds_read_b128 v[176:179], v170 offset:2048
	ds_read_b128 v[180:183], v170 offset:3072
	ds_read_b128 v[184:187], v171
	ds_read_b128 v[188:191], v171 offset:1024
	ds_read_b128 v[192:195], v171 offset:2048
	ds_read_b128 v[196:199], v171 offset:3072
	s_add_u32 s72, s6, 0xfffc0080
	s_addc_u32 s73, s7, -1
	s_cmp_eq_u32 s76, 12
	s_cselect_b32 s75, s13, s73
	s_cselect_b32 s74, s34, s72
	s_cselect_b32 s73, s61, s67
	s_cselect_b32 s72, s62, s63
	v_lshl_add_u64 v[142:143], s[6:7], 0, v[130:131]
	s_add_i32 m0, s1, 0xc000
	ds_read_b128 v[200:203], v172
	ds_read_b128 v[204:207], v172 offset:1024
	ds_read_b128 v[208:211], v172 offset:2048
	ds_read_b128 v[212:215], v172 offset:3072
	ds_read_b128 v[216:219], v172 offset:4096
	ds_read_b128 v[220:223], v172 offset:5120
	ds_read_b128 v[224:227], v172 offset:6144
	ds_read_b128 v[228:231], v172 offset:7168
	global_load_lds_dwordx4 v[142:143], off
	v_lshl_add_u64 v[142:143], s[6:7], 0, v[132:133]
	s_add_i32 m0, s1, 0xe000
	s_nop 0
	global_load_lds_dwordx4 v[142:143], off
	s_waitcnt vmcnt(8) lgkmcnt(0)
	s_barrier
	s_setprio 1
	v_mfma_f32_16x16x32_bf16 v[124:127], v[138:141], v[200:203], v[124:127]
	v_mfma_f32_16x16x32_bf16 v[120:123], v[176:179], v[200:203], v[120:123]
	v_mfma_f32_16x16x32_bf16 v[108:111], v[138:141], v[208:211], v[108:111]
	v_mfma_f32_16x16x32_bf16 v[104:107], v[176:179], v[208:211], v[104:107]
	v_mfma_f32_16x16x32_bf16 v[92:95], v[138:141], v[216:219], v[92:95]
	v_mfma_f32_16x16x32_bf16 v[88:91], v[176:179], v[216:219], v[88:91]
	v_mfma_f32_16x16x32_bf16 v[76:79], v[138:141], v[224:227], v[76:79]
	v_mfma_f32_16x16x32_bf16 v[72:75], v[176:179], v[224:227], v[72:75]
	v_mfma_f32_16x16x32_bf16 v[124:127], v[152:155], v[204:207], v[124:127]
	v_mfma_f32_16x16x32_bf16 v[120:123], v[180:183], v[204:207], v[120:123]
	v_mfma_f32_16x16x32_bf16 v[108:111], v[152:155], v[212:215], v[108:111]
	v_mfma_f32_16x16x32_bf16 v[104:107], v[180:183], v[212:215], v[104:107]
	v_mfma_f32_16x16x32_bf16 v[92:95], v[152:155], v[220:223], v[92:95]
	v_mfma_f32_16x16x32_bf16 v[88:91], v[180:183], v[220:223], v[88:91]
	v_mfma_f32_16x16x32_bf16 v[76:79], v[152:155], v[228:231], v[76:79]
	v_mfma_f32_16x16x32_bf16 v[72:75], v[180:183], v[228:231], v[72:75]
	v_mfma_f32_16x16x32_bf16 v[116:119], v[184:187], v[200:203], v[116:119]
	v_mfma_f32_16x16x32_bf16 v[112:115], v[192:195], v[200:203], v[112:115]
	v_mfma_f32_16x16x32_bf16 v[100:103], v[184:187], v[208:211], v[100:103]
	v_mfma_f32_16x16x32_bf16 v[96:99], v[192:195], v[208:211], v[96:99]
	v_mfma_f32_16x16x32_bf16 v[84:87], v[184:187], v[216:219], v[84:87]
	v_mfma_f32_16x16x32_bf16 v[80:83], v[192:195], v[216:219], v[80:83]
	v_mfma_f32_16x16x32_bf16 v[68:71], v[184:187], v[224:227], v[68:71]
	v_mfma_f32_16x16x32_bf16 v[64:67], v[192:195], v[224:227], v[64:67]
	v_mfma_f32_16x16x32_bf16 v[116:119], v[188:191], v[204:207], v[116:119]
	v_mfma_f32_16x16x32_bf16 v[112:115], v[196:199], v[204:207], v[112:115]
	v_mfma_f32_16x16x32_bf16 v[100:103], v[188:191], v[212:215], v[100:103]
	v_mfma_f32_16x16x32_bf16 v[96:99], v[196:199], v[212:215], v[96:99]
	v_mfma_f32_16x16x32_bf16 v[84:87], v[188:191], v[220:223], v[84:87]
	v_mfma_f32_16x16x32_bf16 v[80:83], v[196:199], v[220:223], v[80:83]
	v_mfma_f32_16x16x32_bf16 v[68:71], v[188:191], v[228:231], v[68:71]
	v_mfma_f32_16x16x32_bf16 v[64:67], v[196:199], v[228:231], v[64:67]
	s_setprio 0
	s_barrier
	s_add_i32 s77, s56, s0
	v_lshl_add_u64 v[142:143], s[72:73], 0, v[146:147]
	s_mov_b32 m0, s77
	ds_read_b128 v[200:203], v172 offset:16384
	ds_read_b128 v[204:207], v172 offset:17408
	ds_read_b128 v[208:211], v172 offset:18432
	ds_read_b128 v[212:215], v172 offset:19456
	ds_read_b128 v[216:219], v172 offset:20480
	ds_read_b128 v[220:223], v172 offset:21504
	ds_read_b128 v[224:227], v172 offset:22528
	ds_read_b128 v[228:231], v172 offset:23552
	global_load_lds_dwordx4 v[142:143], off
	s_add_i32 m0, s77, 0x2000
	s_add_u32 s78, s72, 0x40000
	v_lshl_add_u64 v[232:233], s[72:73], 0, v[150:151]
	s_addc_u32 s79, s73, 0
	s_add_i32 s77, s57, s0
	global_load_lds_dwordx4 v[232:233], off
	v_lshl_add_u64 v[234:235], s[78:79], 0, v[146:147]
	s_mov_b32 m0, s77
	v_lshl_add_u64 v[236:237], s[74:75], 0, v[148:149]
	global_load_lds_dwordx4 v[234:235], off
	v_lshl_add_u64 v[234:235], s[78:79], 0, v[150:151]
	s_add_i32 m0, s77, 0x2000
	s_nop 0
	global_load_lds_dwordx4 v[234:235], off
	v_lshl_add_u64 v[234:235], s[74:75], 0, v[144:145]
	s_mov_b32 m0, s1
	s_nop 0
	global_load_lds_dwordx4 v[234:235], off
	s_mov_b32 m0, s14
	s_nop 0
	global_load_lds_dwordx4 v[236:237], off
	s_waitcnt vmcnt(8) lgkmcnt(0)
	s_barrier
	s_setprio 1
	v_mfma_f32_16x16x32_bf16 v[60:63], v[138:141], v[200:203], v[60:63]
	v_mfma_f32_16x16x32_bf16 v[56:59], v[176:179], v[200:203], v[56:59]
	v_mfma_f32_16x16x32_bf16 v[44:47], v[138:141], v[208:211], v[44:47]
	v_mfma_f32_16x16x32_bf16 v[40:43], v[176:179], v[208:211], v[40:43]
	v_mfma_f32_16x16x32_bf16 v[28:31], v[138:141], v[216:219], v[28:31]
	v_mfma_f32_16x16x32_bf16 v[24:27], v[176:179], v[216:219], v[24:27]
	v_mfma_f32_16x16x32_bf16 v[12:15], v[138:141], v[224:227], v[12:15]
	v_mfma_f32_16x16x32_bf16 v[8:11], v[176:179], v[224:227], v[8:11]
	v_mfma_f32_16x16x32_bf16 v[60:63], v[152:155], v[204:207], v[60:63]
	v_mfma_f32_16x16x32_bf16 v[56:59], v[180:183], v[204:207], v[56:59]
	v_mfma_f32_16x16x32_bf16 v[44:47], v[152:155], v[212:215], v[44:47]
	v_mfma_f32_16x16x32_bf16 v[40:43], v[180:183], v[212:215], v[40:43]
	v_mfma_f32_16x16x32_bf16 v[28:31], v[152:155], v[220:223], v[28:31]
	v_mfma_f32_16x16x32_bf16 v[24:27], v[180:183], v[220:223], v[24:27]
	v_mfma_f32_16x16x32_bf16 v[12:15], v[152:155], v[228:231], v[12:15]
	v_mfma_f32_16x16x32_bf16 v[8:11], v[180:183], v[228:231], v[8:11]
	v_mfma_f32_16x16x32_bf16 v[52:55], v[184:187], v[200:203], v[52:55]
	v_mfma_f32_16x16x32_bf16 v[48:51], v[192:195], v[200:203], v[48:51]
	v_mfma_f32_16x16x32_bf16 v[36:39], v[184:187], v[208:211], v[36:39]
	v_mfma_f32_16x16x32_bf16 v[32:35], v[192:195], v[208:211], v[32:35]
	v_mfma_f32_16x16x32_bf16 v[20:23], v[184:187], v[216:219], v[20:23]
	v_mfma_f32_16x16x32_bf16 v[16:19], v[192:195], v[216:219], v[16:19]
	v_mfma_f32_16x16x32_bf16 v[4:7], v[184:187], v[224:227], v[4:7]
	v_mfma_f32_16x16x32_bf16 v[0:3], v[192:195], v[224:227], v[0:3]
	v_mfma_f32_16x16x32_bf16 v[52:55], v[188:191], v[204:207], v[52:55]
	v_mfma_f32_16x16x32_bf16 v[48:51], v[196:199], v[204:207], v[48:51]
	v_mfma_f32_16x16x32_bf16 v[36:39], v[188:191], v[212:215], v[36:39]
	v_mfma_f32_16x16x32_bf16 v[32:35], v[196:199], v[212:215], v[32:35]
	v_mfma_f32_16x16x32_bf16 v[20:23], v[188:191], v[220:223], v[20:23]
	v_mfma_f32_16x16x32_bf16 v[16:19], v[196:199], v[220:223], v[16:19]
	v_mfma_f32_16x16x32_bf16 v[4:7], v[188:191], v[228:231], v[4:7]
	v_mfma_f32_16x16x32_bf16 v[0:3], v[196:199], v[228:231], v[0:3]
	s_setprio 0
	s_barrier
	s_add_i32 s77, 0, 0x18000
	v_add_u32_e32 v129, s77, v168
	s_add_i32 s78, 0, 0x1c000
	ds_read_b128 v[138:141], v129
	ds_read_b128 v[152:155], v129 offset:1024
	ds_read_b128 v[176:179], v129 offset:2048
	ds_read_b128 v[180:183], v129 offset:3072
	v_add_u32_e32 v129, s78, v168
	ds_read_b128 v[184:187], v129
	ds_read_b128 v[188:191], v129 offset:1024
	ds_read_b128 v[192:195], v129 offset:2048
	ds_read_b128 v[196:199], v129 offset:3072
	s_add_u32 s74, s74, 0x40000
	s_addc_u32 s75, s75, 0
	s_mov_b32 m0, s33
	v_lshl_add_u64 v[238:239], s[74:75], 0, v[144:145]
	ds_read_b128 v[200:203], v172 offset:32768
	ds_read_b128 v[204:207], v172 offset:33792
	ds_read_b128 v[208:211], v172 offset:34816
	ds_read_b128 v[212:215], v172 offset:35840
	ds_read_b128 v[216:219], v172 offset:36864
	ds_read_b128 v[220:223], v172 offset:37888
	ds_read_b128 v[224:227], v172 offset:38912
	ds_read_b128 v[228:231], v172 offset:39936
	global_load_lds_dwordx4 v[238:239], off
	v_lshl_add_u64 v[238:239], s[74:75], 0, v[148:149]
	s_mov_b32 m0, s35
	s_nop 0
	global_load_lds_dwordx4 v[238:239], off
	s_waitcnt vmcnt(8) lgkmcnt(0)
	s_barrier
	s_setprio 1
	v_mfma_f32_16x16x32_bf16 v[124:127], v[138:141], v[200:203], v[124:127]
	v_mfma_f32_16x16x32_bf16 v[120:123], v[176:179], v[200:203], v[120:123]
	v_mfma_f32_16x16x32_bf16 v[108:111], v[138:141], v[208:211], v[108:111]
	v_mfma_f32_16x16x32_bf16 v[104:107], v[176:179], v[208:211], v[104:107]
	v_mfma_f32_16x16x32_bf16 v[92:95], v[138:141], v[216:219], v[92:95]
	v_mfma_f32_16x16x32_bf16 v[88:91], v[176:179], v[216:219], v[88:91]
	v_mfma_f32_16x16x32_bf16 v[76:79], v[138:141], v[224:227], v[76:79]
	v_mfma_f32_16x16x32_bf16 v[72:75], v[176:179], v[224:227], v[72:75]
	v_mfma_f32_16x16x32_bf16 v[124:127], v[152:155], v[204:207], v[124:127]
	v_mfma_f32_16x16x32_bf16 v[120:123], v[180:183], v[204:207], v[120:123]
	v_mfma_f32_16x16x32_bf16 v[108:111], v[152:155], v[212:215], v[108:111]
	v_mfma_f32_16x16x32_bf16 v[104:107], v[180:183], v[212:215], v[104:107]
	v_mfma_f32_16x16x32_bf16 v[92:95], v[152:155], v[220:223], v[92:95]
	v_mfma_f32_16x16x32_bf16 v[88:91], v[180:183], v[220:223], v[88:91]
	v_mfma_f32_16x16x32_bf16 v[76:79], v[152:155], v[228:231], v[76:79]
	v_mfma_f32_16x16x32_bf16 v[72:75], v[180:183], v[228:231], v[72:75]
	v_mfma_f32_16x16x32_bf16 v[116:119], v[184:187], v[200:203], v[116:119]
	v_mfma_f32_16x16x32_bf16 v[112:115], v[192:195], v[200:203], v[112:115]
	v_mfma_f32_16x16x32_bf16 v[100:103], v[184:187], v[208:211], v[100:103]
	v_mfma_f32_16x16x32_bf16 v[96:99], v[192:195], v[208:211], v[96:99]
	v_mfma_f32_16x16x32_bf16 v[84:87], v[184:187], v[216:219], v[84:87]
	v_mfma_f32_16x16x32_bf16 v[80:83], v[192:195], v[216:219], v[80:83]
	v_mfma_f32_16x16x32_bf16 v[68:71], v[184:187], v[224:227], v[68:71]
	v_mfma_f32_16x16x32_bf16 v[64:67], v[192:195], v[224:227], v[64:67]
	v_mfma_f32_16x16x32_bf16 v[116:119], v[188:191], v[204:207], v[116:119]
	v_mfma_f32_16x16x32_bf16 v[112:115], v[196:199], v[204:207], v[112:115]
	v_mfma_f32_16x16x32_bf16 v[100:103], v[188:191], v[212:215], v[100:103]
	v_mfma_f32_16x16x32_bf16 v[96:99], v[196:199], v[212:215], v[96:99]
	v_mfma_f32_16x16x32_bf16 v[84:87], v[188:191], v[220:223], v[84:87]
	v_mfma_f32_16x16x32_bf16 v[80:83], v[196:199], v[220:223], v[80:83]
	v_mfma_f32_16x16x32_bf16 v[68:71], v[188:191], v[228:231], v[68:71]
	v_mfma_f32_16x16x32_bf16 v[64:67], v[196:199], v[228:231], v[64:67]
	s_setprio 0
	s_barrier
	s_add_i32 s74, s77, s0
	v_lshl_add_u64 v[142:143], v[142:143], 0, s[10:11]
	s_mov_b32 m0, s74
	ds_read_b128 v[200:203], v172 offset:49152
	ds_read_b128 v[204:207], v172 offset:50176
	ds_read_b128 v[208:211], v172 offset:51200
	ds_read_b128 v[212:215], v172 offset:52224
	ds_read_b128 v[216:219], v172 offset:53248
	ds_read_b128 v[220:223], v172 offset:54272
	ds_read_b128 v[224:227], v172 offset:55296
	ds_read_b128 v[228:231], v172 offset:56320
	global_load_lds_dwordx4 v[142:143], off
	s_add_i32 m0, s74, 0x2000
	s_add_u32 s72, s72, 0x40080
	v_lshl_add_u64 v[142:143], v[232:233], 0, s[10:11]
	s_addc_u32 s73, s73, 0
	s_add_i32 s74, s78, s0
	global_load_lds_dwordx4 v[142:143], off
	v_lshl_add_u64 v[142:143], s[72:73], 0, v[146:147]
	s_mov_b32 m0, s74
	s_nop 0
	global_load_lds_dwordx4 v[142:143], off
	v_lshl_add_u64 v[142:143], s[72:73], 0, v[150:151]
	s_add_i32 m0, s74, 0x2000
	s_nop 0
	global_load_lds_dwordx4 v[142:143], off
	v_lshl_add_u64 v[142:143], v[234:235], 0, s[10:11]
	s_mov_b32 m0, s52
	s_nop 0
	global_load_lds_dwordx4 v[142:143], off
	v_lshl_add_u64 v[142:143], v[236:237], 0, s[10:11]
	s_mov_b32 m0, s53
	s_nop 0
	global_load_lds_dwordx4 v[142:143], off
	s_waitcnt vmcnt(8) lgkmcnt(0)
	s_barrier
	s_setprio 1
	v_mfma_f32_16x16x32_bf16 v[60:63], v[138:141], v[200:203], v[60:63]
	v_mfma_f32_16x16x32_bf16 v[56:59], v[176:179], v[200:203], v[56:59]
	v_mfma_f32_16x16x32_bf16 v[44:47], v[138:141], v[208:211], v[44:47]
	v_mfma_f32_16x16x32_bf16 v[40:43], v[176:179], v[208:211], v[40:43]
	v_mfma_f32_16x16x32_bf16 v[28:31], v[138:141], v[216:219], v[28:31]
	v_mfma_f32_16x16x32_bf16 v[24:27], v[176:179], v[216:219], v[24:27]
	v_mfma_f32_16x16x32_bf16 v[12:15], v[138:141], v[224:227], v[12:15]
	v_mfma_f32_16x16x32_bf16 v[8:11], v[176:179], v[224:227], v[8:11]
	v_mfma_f32_16x16x32_bf16 v[60:63], v[152:155], v[204:207], v[60:63]
	v_mfma_f32_16x16x32_bf16 v[56:59], v[180:183], v[204:207], v[56:59]
	v_mfma_f32_16x16x32_bf16 v[44:47], v[152:155], v[212:215], v[44:47]
	v_mfma_f32_16x16x32_bf16 v[40:43], v[180:183], v[212:215], v[40:43]
	v_mfma_f32_16x16x32_bf16 v[28:31], v[152:155], v[220:223], v[28:31]
	v_mfma_f32_16x16x32_bf16 v[24:27], v[180:183], v[220:223], v[24:27]
	v_mfma_f32_16x16x32_bf16 v[12:15], v[152:155], v[228:231], v[12:15]
	v_mfma_f32_16x16x32_bf16 v[8:11], v[180:183], v[228:231], v[8:11]
	v_mfma_f32_16x16x32_bf16 v[52:55], v[184:187], v[200:203], v[52:55]
	v_mfma_f32_16x16x32_bf16 v[48:51], v[192:195], v[200:203], v[48:51]
	v_mfma_f32_16x16x32_bf16 v[36:39], v[184:187], v[208:211], v[36:39]
	v_mfma_f32_16x16x32_bf16 v[32:35], v[192:195], v[208:211], v[32:35]
	v_mfma_f32_16x16x32_bf16 v[20:23], v[184:187], v[216:219], v[20:23]
	v_mfma_f32_16x16x32_bf16 v[16:19], v[192:195], v[216:219], v[16:19]
	v_mfma_f32_16x16x32_bf16 v[4:7], v[184:187], v[224:227], v[4:7]
	v_mfma_f32_16x16x32_bf16 v[0:3], v[192:195], v[224:227], v[0:3]
	v_mfma_f32_16x16x32_bf16 v[52:55], v[188:191], v[204:207], v[52:55]
	v_mfma_f32_16x16x32_bf16 v[48:51], v[196:199], v[204:207], v[48:51]
	v_mfma_f32_16x16x32_bf16 v[36:39], v[188:191], v[212:215], v[36:39]
	v_mfma_f32_16x16x32_bf16 v[32:35], v[196:199], v[212:215], v[32:35]
	v_mfma_f32_16x16x32_bf16 v[20:23], v[188:191], v[220:223], v[20:23]
	v_mfma_f32_16x16x32_bf16 v[16:19], v[196:199], v[220:223], v[16:19]
	v_mfma_f32_16x16x32_bf16 v[4:7], v[188:191], v[228:231], v[4:7]
	v_mfma_f32_16x16x32_bf16 v[0:3], v[196:199], v[228:231], v[0:3]
	s_setprio 0
	s_barrier
	s_add_i32 s76, s76, 2
	s_add_u32 s6, s6, 0x100
	s_addc_u32 s7, s7, 0
	s_add_u32 s63, s63, 0x100
	s_addc_u32 s67, s67, 0
	s_cmp_gt_u32 s76, 13
	s_cbranch_scc0 .LBB0_153
	s_and_b64 vcc, exec, s[36:37]
	s_cbranch_vccz .LBB0_156
	s_barrier

.LBB0_215:
	ds_read_b128 v[40:43], v182
	ds_read_b128 v[44:47], v182 offset:1024
	ds_read_b128 v[48:51], v182 offset:2048
	ds_read_b128 v[52:55], v182 offset:3072
	ds_read_b128 v[168:171], v183
	ds_read_b128 v[172:175], v183 offset:1024
	ds_read_b128 v[176:179], v183 offset:2048
	ds_read_b128 v[186:189], v183 offset:3072
	s_add_u32 s76, s74, 0xfffc0080
	s_addc_u32 s77, s75, -1
	s_cmp_eq_u32 s83, 12
	s_cselect_b32 s79, s13, s77
	s_cselect_b32 s78, s34, s76
	s_cselect_b32 s77, s36, s82
	s_cselect_b32 s76, s48, s69
	v_lshl_add_u64 v[222:223], s[74:75], 0, v[158:159]
	s_add_i32 m0, s35, 0xc000
	ds_read_b128 v[190:193], v184
	ds_read_b128 v[194:197], v184 offset:1024
	ds_read_b128 v[198:201], v184 offset:2048
	ds_read_b128 v[202:205], v184 offset:3072
	ds_read_b128 v[206:209], v184 offset:4096
	ds_read_b128 v[210:213], v184 offset:5120
	ds_read_b128 v[214:217], v184 offset:6144
	ds_read_b128 v[218:221], v184 offset:7168
	global_load_lds_dwordx4 v[222:223], off
	v_lshl_add_u64 v[222:223], s[74:75], 0, v[162:163]
	s_add_i32 m0, s35, 0xe000
	s_nop 0
	global_load_lds_dwordx4 v[222:223], off
	s_waitcnt vmcnt(8) lgkmcnt(0)
	s_barrier
	s_setprio 1
	v_mfma_f32_16x16x32_bf16 v[140:143], v[40:43], v[190:193], v[140:143]
	v_mfma_f32_16x16x32_bf16 v[136:139], v[48:51], v[190:193], v[136:139]
	v_mfma_f32_16x16x32_bf16 v[124:127], v[40:43], v[198:201], v[124:127]
	v_mfma_f32_16x16x32_bf16 v[120:123], v[48:51], v[198:201], v[120:123]
	v_mfma_f32_16x16x32_bf16 v[108:111], v[40:43], v[206:209], v[108:111]
	v_mfma_f32_16x16x32_bf16 v[104:107], v[48:51], v[206:209], v[104:107]
	v_mfma_f32_16x16x32_bf16 v[92:95], v[40:43], v[214:217], v[92:95]
	v_mfma_f32_16x16x32_bf16 v[88:91], v[48:51], v[214:217], v[88:91]
	v_mfma_f32_16x16x32_bf16 v[140:143], v[44:47], v[194:197], v[140:143]
	v_mfma_f32_16x16x32_bf16 v[136:139], v[52:55], v[194:197], v[136:139]
	v_mfma_f32_16x16x32_bf16 v[124:127], v[44:47], v[202:205], v[124:127]
	v_mfma_f32_16x16x32_bf16 v[120:123], v[52:55], v[202:205], v[120:123]
	v_mfma_f32_16x16x32_bf16 v[108:111], v[44:47], v[210:213], v[108:111]
	v_mfma_f32_16x16x32_bf16 v[104:107], v[52:55], v[210:213], v[104:107]
	v_mfma_f32_16x16x32_bf16 v[92:95], v[44:47], v[218:221], v[92:95]
	v_mfma_f32_16x16x32_bf16 v[88:91], v[52:55], v[218:221], v[88:91]
	v_mfma_f32_16x16x32_bf16 v[132:135], v[168:171], v[190:193], v[132:135]
	v_mfma_f32_16x16x32_bf16 v[128:131], v[176:179], v[190:193], v[128:131]
	v_mfma_f32_16x16x32_bf16 v[116:119], v[168:171], v[198:201], v[116:119]
	v_mfma_f32_16x16x32_bf16 v[112:115], v[176:179], v[198:201], v[112:115]
	v_mfma_f32_16x16x32_bf16 v[100:103], v[168:171], v[206:209], v[100:103]
	v_mfma_f32_16x16x32_bf16 v[96:99], v[176:179], v[206:209], v[96:99]
	v_mfma_f32_16x16x32_bf16 v[84:87], v[168:171], v[214:217], v[84:87]
	v_mfma_f32_16x16x32_bf16 v[80:83], v[176:179], v[214:217], v[80:83]
	v_mfma_f32_16x16x32_bf16 v[132:135], v[172:175], v[194:197], v[132:135]
	v_mfma_f32_16x16x32_bf16 v[128:131], v[186:189], v[194:197], v[128:131]
	v_mfma_f32_16x16x32_bf16 v[116:119], v[172:175], v[202:205], v[116:119]
	v_mfma_f32_16x16x32_bf16 v[112:115], v[186:189], v[202:205], v[112:115]
	v_mfma_f32_16x16x32_bf16 v[100:103], v[172:175], v[210:213], v[100:103]
	v_mfma_f32_16x16x32_bf16 v[96:99], v[186:189], v[210:213], v[96:99]
	v_mfma_f32_16x16x32_bf16 v[84:87], v[172:175], v[218:221], v[84:87]
	v_mfma_f32_16x16x32_bf16 v[80:83], v[186:189], v[218:221], v[80:83]
	s_setprio 0
	s_barrier
	s_add_i32 s84, s57, s14
	v_lshl_add_u64 v[222:223], s[76:77], 0, v[146:147]
	s_mov_b32 m0, s84
	ds_read_b128 v[190:193], v184 offset:16384
	ds_read_b128 v[194:197], v184 offset:17408
	ds_read_b128 v[198:201], v184 offset:18432
	ds_read_b128 v[202:205], v184 offset:19456
	ds_read_b128 v[206:209], v184 offset:20480
	ds_read_b128 v[210:213], v184 offset:21504
	ds_read_b128 v[214:217], v184 offset:22528
	ds_read_b128 v[218:221], v184 offset:23552
	global_load_lds_dwordx4 v[222:223], off
	s_add_i32 m0, s84, 0x2000
	s_add_u32 s84, s76, 0x40000
	v_lshl_add_u64 v[224:225], s[76:77], 0, v[150:151]
	s_addc_u32 s85, s77, 0
	s_add_i32 s86, s60, s14
	global_load_lds_dwordx4 v[224:225], off
	v_lshl_add_u64 v[226:227], s[84:85], 0, v[146:147]
	s_mov_b32 m0, s86
	v_lshl_add_u64 v[228:229], s[78:79], 0, v[148:149]
	global_load_lds_dwordx4 v[226:227], off
	v_lshl_add_u64 v[226:227], s[84:85], 0, v[150:151]
	s_add_i32 m0, s86, 0x2000
	s_nop 0
	global_load_lds_dwordx4 v[226:227], off
	v_lshl_add_u64 v[226:227], s[78:79], 0, v[144:145]
	s_mov_b32 m0, s35
	s_nop 0
	global_load_lds_dwordx4 v[226:227], off
	s_mov_b32 m0, s42
	s_nop 0
	global_load_lds_dwordx4 v[228:229], off
	s_waitcnt vmcnt(8) lgkmcnt(0)
	s_barrier
	s_setprio 1
	v_mfma_f32_16x16x32_bf16 v[76:79], v[40:43], v[190:193], v[76:79]
	v_mfma_f32_16x16x32_bf16 v[72:75], v[48:51], v[190:193], v[72:75]
	v_mfma_f32_16x16x32_bf16 v[60:63], v[40:43], v[198:201], v[60:63]
	v_mfma_f32_16x16x32_bf16 v[56:59], v[48:51], v[198:201], v[56:59]
	v_mfma_f32_16x16x32_bf16 v[28:31], v[40:43], v[206:209], v[28:31]
	v_mfma_f32_16x16x32_bf16 v[24:27], v[48:51], v[206:209], v[24:27]
	v_mfma_f32_16x16x32_bf16 v[12:15], v[40:43], v[214:217], v[12:15]
	v_mfma_f32_16x16x32_bf16 v[8:11], v[48:51], v[214:217], v[8:11]
	v_mfma_f32_16x16x32_bf16 v[76:79], v[44:47], v[194:197], v[76:79]
	v_mfma_f32_16x16x32_bf16 v[72:75], v[52:55], v[194:197], v[72:75]
	v_mfma_f32_16x16x32_bf16 v[60:63], v[44:47], v[202:205], v[60:63]
	v_mfma_f32_16x16x32_bf16 v[56:59], v[52:55], v[202:205], v[56:59]
	v_mfma_f32_16x16x32_bf16 v[28:31], v[44:47], v[210:213], v[28:31]
	v_mfma_f32_16x16x32_bf16 v[24:27], v[52:55], v[210:213], v[24:27]
	v_mfma_f32_16x16x32_bf16 v[12:15], v[44:47], v[218:221], v[12:15]
	v_mfma_f32_16x16x32_bf16 v[8:11], v[52:55], v[218:221], v[8:11]
	v_mfma_f32_16x16x32_bf16 v[36:39], v[168:171], v[198:201], v[36:39]
	v_mfma_f32_16x16x32_bf16 v[32:35], v[176:179], v[198:201], v[32:35]
	v_mfma_f32_16x16x32_bf16 v[20:23], v[168:171], v[206:209], v[20:23]
	v_mfma_f32_16x16x32_bf16 v[16:19], v[176:179], v[206:209], v[16:19]
	v_mfma_f32_16x16x32_bf16 v[4:7], v[168:171], v[214:217], v[4:7]
	v_mfma_f32_16x16x32_bf16 v[0:3], v[176:179], v[214:217], v[0:3]
	v_mfma_f32_16x16x32_bf16 v[40:43], v[168:171], v[190:193], v[68:71]
	v_mfma_f32_16x16x32_bf16 v[44:47], v[176:179], v[190:193], v[64:67]
	v_mfma_f32_16x16x32_bf16 v[36:39], v[172:175], v[202:205], v[36:39]
	v_mfma_f32_16x16x32_bf16 v[32:35], v[186:189], v[202:205], v[32:35]
	v_mfma_f32_16x16x32_bf16 v[20:23], v[172:175], v[210:213], v[20:23]
	v_mfma_f32_16x16x32_bf16 v[16:19], v[186:189], v[210:213], v[16:19]
	v_mfma_f32_16x16x32_bf16 v[4:7], v[172:175], v[218:221], v[4:7]
	v_mfma_f32_16x16x32_bf16 v[0:3], v[186:189], v[218:221], v[0:3]
	v_mfma_f32_16x16x32_bf16 v[40:43], v[172:175], v[194:197], v[40:43]
	v_mfma_f32_16x16x32_bf16 v[44:47], v[186:189], v[194:197], v[44:47]
	s_setprio 0
	s_barrier
	s_add_i32 s84, 0, 0x18000
	s_add_i32 s85, 0, 0x1c000
	v_add_u32_e32 v68, s84, v180
	v_add_u32_e32 v152, s85, v180
	ds_read_b128 v[48:51], v68
	ds_read_b128 v[52:55], v68 offset:1024
	ds_read_b128 v[64:67], v68 offset:2048
	ds_read_b128 v[68:71], v68 offset:3072
	ds_read_b128 v[168:171], v152
	ds_read_b128 v[172:175], v152 offset:1024
	ds_read_b128 v[176:179], v152 offset:2048
	ds_read_b128 v[186:189], v152 offset:3072
	s_add_u32 s78, s78, 0x40000
	s_addc_u32 s79, s79, 0
	s_mov_b32 m0, s49
	v_lshl_add_u64 v[230:231], s[78:79], 0, v[144:145]
	ds_read_b128 v[190:193], v184 offset:32768
	ds_read_b128 v[194:197], v184 offset:33792
	ds_read_b128 v[198:201], v184 offset:34816
	ds_read_b128 v[202:205], v184 offset:35840
	ds_read_b128 v[206:209], v184 offset:36864
	ds_read_b128 v[210:213], v184 offset:37888
	ds_read_b128 v[214:217], v184 offset:38912
	ds_read_b128 v[218:221], v184 offset:39936
	global_load_lds_dwordx4 v[230:231], off
	v_lshl_add_u64 v[230:231], s[78:79], 0, v[148:149]
	s_mov_b32 m0, s50
	s_nop 0
	global_load_lds_dwordx4 v[230:231], off
	s_waitcnt vmcnt(8) lgkmcnt(0)
	s_barrier
	s_setprio 1
	v_mfma_f32_16x16x32_bf16 v[140:143], v[48:51], v[190:193], v[140:143]
	v_mfma_f32_16x16x32_bf16 v[136:139], v[64:67], v[190:193], v[136:139]
	v_mfma_f32_16x16x32_bf16 v[124:127], v[48:51], v[198:201], v[124:127]
	v_mfma_f32_16x16x32_bf16 v[120:123], v[64:67], v[198:201], v[120:123]
	v_mfma_f32_16x16x32_bf16 v[108:111], v[48:51], v[206:209], v[108:111]
	v_mfma_f32_16x16x32_bf16 v[104:107], v[64:67], v[206:209], v[104:107]
	v_mfma_f32_16x16x32_bf16 v[92:95], v[48:51], v[214:217], v[92:95]
	v_mfma_f32_16x16x32_bf16 v[88:91], v[64:67], v[214:217], v[88:91]
	v_mfma_f32_16x16x32_bf16 v[140:143], v[52:55], v[194:197], v[140:143]
	v_mfma_f32_16x16x32_bf16 v[136:139], v[68:71], v[194:197], v[136:139]
	v_mfma_f32_16x16x32_bf16 v[124:127], v[52:55], v[202:205], v[124:127]
	v_mfma_f32_16x16x32_bf16 v[120:123], v[68:71], v[202:205], v[120:123]
	v_mfma_f32_16x16x32_bf16 v[108:111], v[52:55], v[210:213], v[108:111]
	v_mfma_f32_16x16x32_bf16 v[104:107], v[68:71], v[210:213], v[104:107]
	v_mfma_f32_16x16x32_bf16 v[92:95], v[52:55], v[218:221], v[92:95]
	v_mfma_f32_16x16x32_bf16 v[88:91], v[68:71], v[218:221], v[88:91]
	v_mfma_f32_16x16x32_bf16 v[132:135], v[168:171], v[190:193], v[132:135]
	v_mfma_f32_16x16x32_bf16 v[128:131], v[176:179], v[190:193], v[128:131]
	v_mfma_f32_16x16x32_bf16 v[116:119], v[168:171], v[198:201], v[116:119]
	v_mfma_f32_16x16x32_bf16 v[112:115], v[176:179], v[198:201], v[112:115]
	v_mfma_f32_16x16x32_bf16 v[100:103], v[168:171], v[206:209], v[100:103]
	v_mfma_f32_16x16x32_bf16 v[96:99], v[176:179], v[206:209], v[96:99]
	v_mfma_f32_16x16x32_bf16 v[84:87], v[168:171], v[214:217], v[84:87]
	v_mfma_f32_16x16x32_bf16 v[80:83], v[176:179], v[214:217], v[80:83]
	v_mfma_f32_16x16x32_bf16 v[132:135], v[172:175], v[194:197], v[132:135]
	v_mfma_f32_16x16x32_bf16 v[128:131], v[186:189], v[194:197], v[128:131]
	v_mfma_f32_16x16x32_bf16 v[116:119], v[172:175], v[202:205], v[116:119]
	v_mfma_f32_16x16x32_bf16 v[112:115], v[186:189], v[202:205], v[112:115]
	v_mfma_f32_16x16x32_bf16 v[100:103], v[172:175], v[210:213], v[100:103]
	v_mfma_f32_16x16x32_bf16 v[96:99], v[186:189], v[210:213], v[96:99]
	v_mfma_f32_16x16x32_bf16 v[84:87], v[172:175], v[218:221], v[84:87]
	v_mfma_f32_16x16x32_bf16 v[80:83], v[186:189], v[218:221], v[80:83]
	s_setprio 0
	s_barrier
	s_add_i32 s78, s84, s14
	v_lshl_add_u64 v[222:223], v[222:223], 0, s[40:41]
	s_mov_b32 m0, s78
	ds_read_b128 v[190:193], v184 offset:49152
	ds_read_b128 v[194:197], v184 offset:50176
	ds_read_b128 v[198:201], v184 offset:51200
	ds_read_b128 v[202:205], v184 offset:52224
	ds_read_b128 v[206:209], v184 offset:53248
	ds_read_b128 v[210:213], v184 offset:54272
	ds_read_b128 v[214:217], v184 offset:55296
	ds_read_b128 v[218:221], v184 offset:56320
	global_load_lds_dwordx4 v[222:223], off
	s_add_i32 m0, s78, 0x2000
	s_add_u32 s76, s76, 0x40080
	v_lshl_add_u64 v[222:223], v[224:225], 0, s[40:41]
	s_addc_u32 s77, s77, 0
	s_add_i32 s78, s85, s14
	global_load_lds_dwordx4 v[222:223], off
	v_lshl_add_u64 v[222:223], s[76:77], 0, v[146:147]
	s_mov_b32 m0, s78
	s_nop 0
	global_load_lds_dwordx4 v[222:223], off
	v_lshl_add_u64 v[222:223], s[76:77], 0, v[150:151]
	s_add_i32 m0, s78, 0x2000
	s_nop 0
	global_load_lds_dwordx4 v[222:223], off
	v_lshl_add_u64 v[222:223], v[226:227], 0, s[40:41]
	s_mov_b32 m0, s52
	s_nop 0
	global_load_lds_dwordx4 v[222:223], off
	v_lshl_add_u64 v[222:223], v[228:229], 0, s[40:41]
	s_mov_b32 m0, s53
	s_nop 0
	global_load_lds_dwordx4 v[222:223], off
	s_waitcnt vmcnt(8) lgkmcnt(0)
	s_barrier
	s_setprio 1
	v_mfma_f32_16x16x32_bf16 v[76:79], v[48:51], v[190:193], v[76:79]
	v_mfma_f32_16x16x32_bf16 v[72:75], v[64:67], v[190:193], v[72:75]
	v_mfma_f32_16x16x32_bf16 v[60:63], v[48:51], v[198:201], v[60:63]
	v_mfma_f32_16x16x32_bf16 v[56:59], v[64:67], v[198:201], v[56:59]
	v_mfma_f32_16x16x32_bf16 v[28:31], v[48:51], v[206:209], v[28:31]
	v_mfma_f32_16x16x32_bf16 v[24:27], v[64:67], v[206:209], v[24:27]
	v_mfma_f32_16x16x32_bf16 v[12:15], v[48:51], v[214:217], v[12:15]
	v_mfma_f32_16x16x32_bf16 v[8:11], v[64:67], v[214:217], v[8:11]
	v_mfma_f32_16x16x32_bf16 v[76:79], v[52:55], v[194:197], v[76:79]
	v_mfma_f32_16x16x32_bf16 v[72:75], v[68:71], v[194:197], v[72:75]
	v_mfma_f32_16x16x32_bf16 v[60:63], v[52:55], v[202:205], v[60:63]
	v_mfma_f32_16x16x32_bf16 v[56:59], v[68:71], v[202:205], v[56:59]
	v_mfma_f32_16x16x32_bf16 v[28:31], v[52:55], v[210:213], v[28:31]
	v_mfma_f32_16x16x32_bf16 v[24:27], v[68:71], v[210:213], v[24:27]
	v_mfma_f32_16x16x32_bf16 v[12:15], v[52:55], v[218:221], v[12:15]
	v_mfma_f32_16x16x32_bf16 v[8:11], v[68:71], v[218:221], v[8:11]
	v_mfma_f32_16x16x32_bf16 v[40:43], v[168:171], v[190:193], v[40:43]
	v_mfma_f32_16x16x32_bf16 v[68:71], v[172:175], v[194:197], v[40:43]
	v_mfma_f32_16x16x32_bf16 v[40:43], v[176:179], v[190:193], v[44:47]
	v_mfma_f32_16x16x32_bf16 v[36:39], v[168:171], v[198:201], v[36:39]
	v_mfma_f32_16x16x32_bf16 v[32:35], v[176:179], v[198:201], v[32:35]
	v_mfma_f32_16x16x32_bf16 v[20:23], v[168:171], v[206:209], v[20:23]
	v_mfma_f32_16x16x32_bf16 v[16:19], v[176:179], v[206:209], v[16:19]
	v_mfma_f32_16x16x32_bf16 v[4:7], v[168:171], v[214:217], v[4:7]
	v_mfma_f32_16x16x32_bf16 v[0:3], v[176:179], v[214:217], v[0:3]
	v_mfma_f32_16x16x32_bf16 v[64:67], v[186:189], v[194:197], v[40:43]
	v_mfma_f32_16x16x32_bf16 v[36:39], v[172:175], v[202:205], v[36:39]
	v_mfma_f32_16x16x32_bf16 v[32:35], v[186:189], v[202:205], v[32:35]
	v_mfma_f32_16x16x32_bf16 v[20:23], v[172:175], v[210:213], v[20:23]
	v_mfma_f32_16x16x32_bf16 v[16:19], v[186:189], v[210:213], v[16:19]
	v_mfma_f32_16x16x32_bf16 v[4:7], v[172:175], v[218:221], v[4:7]
	v_mfma_f32_16x16x32_bf16 v[0:3], v[186:189], v[218:221], v[0:3]
	s_setprio 0
	s_barrier
	s_add_i32 s83, s83, 2
	s_add_u32 s74, s74, 0x100
	s_addc_u32 s75, s75, 0
	s_add_u32 s69, s69, 0x100
	s_addc_u32 s82, s82, 0
	s_cmp_gt_u32 s83, 13
	s_cbranch_scc0 .LBB0_215
	s_and_b64 vcc, exec, s[66:67]
	s_cbranch_vccz .LBB0_218
	s_barrier

.LBB0_649:
	ds_read_b128 v[146:149], v155
	ds_read_b128 v[162:165], v155 offset:1024
	ds_read_b128 v[166:169], v155 offset:2048
	ds_read_b128 v[170:173], v155 offset:3072
	ds_read_b128 v[174:177], v156
	ds_read_b128 v[178:181], v156 offset:1024
	ds_read_b128 v[182:185], v156 offset:2048
	ds_read_b128 v[186:189], v156 offset:3072
	s_add_u32 s40, s38, 0xfffc0080
	s_addc_u32 s41, s39, -1
	s_cmp_eq_u32 s69, 12
	s_cselect_b32 s65, s29, s41
	s_cselect_b32 s64, s62, s40
	s_cselect_b32 s41, s63, s68
	s_cselect_b32 s40, s66, s67
	v_lshl_add_u64 v[150:151], s[38:39], 0, v[138:139]
	s_add_i32 m0, s1, 0xc000
	ds_read_b128 v[190:193], v157
	ds_read_b128 v[194:197], v157 offset:1024
	ds_read_b128 v[198:201], v157 offset:2048
	ds_read_b128 v[202:205], v157 offset:3072
	ds_read_b128 v[206:209], v157 offset:4096
	ds_read_b128 v[210:213], v157 offset:5120
	ds_read_b128 v[214:217], v157 offset:6144
	ds_read_b128 v[218:221], v157 offset:7168
	global_load_lds_dwordx4 v[150:151], off
	v_lshl_add_u64 v[150:151], s[38:39], 0, v[140:141]
	s_add_i32 m0, s1, 0xe000
	s_nop 0
	global_load_lds_dwordx4 v[150:151], off
	s_waitcnt vmcnt(8) lgkmcnt(0)
	s_barrier
	s_setprio 1
	v_mfma_f32_16x16x32_bf16 v[124:127], v[146:149], v[190:193], v[124:127]
	v_mfma_f32_16x16x32_bf16 v[120:123], v[166:169], v[190:193], v[120:123]
	v_mfma_f32_16x16x32_bf16 v[108:111], v[146:149], v[198:201], v[108:111]
	v_mfma_f32_16x16x32_bf16 v[104:107], v[166:169], v[198:201], v[104:107]
	v_mfma_f32_16x16x32_bf16 v[92:95], v[146:149], v[206:209], v[92:95]
	v_mfma_f32_16x16x32_bf16 v[88:91], v[166:169], v[206:209], v[88:91]
	v_mfma_f32_16x16x32_bf16 v[76:79], v[146:149], v[214:217], v[76:79]
	v_mfma_f32_16x16x32_bf16 v[72:75], v[166:169], v[214:217], v[72:75]
	v_mfma_f32_16x16x32_bf16 v[124:127], v[162:165], v[194:197], v[124:127]
	v_mfma_f32_16x16x32_bf16 v[120:123], v[170:173], v[194:197], v[120:123]
	v_mfma_f32_16x16x32_bf16 v[108:111], v[162:165], v[202:205], v[108:111]
	v_mfma_f32_16x16x32_bf16 v[104:107], v[170:173], v[202:205], v[104:107]
	v_mfma_f32_16x16x32_bf16 v[92:95], v[162:165], v[210:213], v[92:95]
	v_mfma_f32_16x16x32_bf16 v[88:91], v[170:173], v[210:213], v[88:91]
	v_mfma_f32_16x16x32_bf16 v[76:79], v[162:165], v[218:221], v[76:79]
	v_mfma_f32_16x16x32_bf16 v[72:75], v[170:173], v[218:221], v[72:75]
	v_mfma_f32_16x16x32_bf16 v[116:119], v[174:177], v[190:193], v[116:119]
	v_mfma_f32_16x16x32_bf16 v[112:115], v[182:185], v[190:193], v[112:115]
	v_mfma_f32_16x16x32_bf16 v[100:103], v[174:177], v[198:201], v[100:103]
	v_mfma_f32_16x16x32_bf16 v[96:99], v[182:185], v[198:201], v[96:99]
	v_mfma_f32_16x16x32_bf16 v[84:87], v[174:177], v[206:209], v[84:87]
	v_mfma_f32_16x16x32_bf16 v[80:83], v[182:185], v[206:209], v[80:83]
	v_mfma_f32_16x16x32_bf16 v[68:71], v[174:177], v[214:217], v[68:71]
	v_mfma_f32_16x16x32_bf16 v[64:67], v[182:185], v[214:217], v[64:67]
	v_mfma_f32_16x16x32_bf16 v[116:119], v[178:181], v[194:197], v[116:119]
	v_mfma_f32_16x16x32_bf16 v[112:115], v[186:189], v[194:197], v[112:115]
	v_mfma_f32_16x16x32_bf16 v[100:103], v[178:181], v[202:205], v[100:103]
	v_mfma_f32_16x16x32_bf16 v[96:99], v[186:189], v[202:205], v[96:99]
	v_mfma_f32_16x16x32_bf16 v[84:87], v[178:181], v[210:213], v[84:87]
	v_mfma_f32_16x16x32_bf16 v[80:83], v[186:189], v[210:213], v[80:83]
	v_mfma_f32_16x16x32_bf16 v[68:71], v[178:181], v[218:221], v[68:71]
	v_mfma_f32_16x16x32_bf16 v[64:67], v[186:189], v[218:221], v[64:67]
	s_setprio 0
	s_barrier
	s_add_i32 s70, s51, s0
	v_lshl_add_u64 v[150:151], s[40:41], 0, v[130:131]
	s_mov_b32 m0, s70
	ds_read_b128 v[190:193], v157 offset:16384
	ds_read_b128 v[194:197], v157 offset:17408
	ds_read_b128 v[198:201], v157 offset:18432
	ds_read_b128 v[202:205], v157 offset:19456
	ds_read_b128 v[206:209], v157 offset:20480
	ds_read_b128 v[210:213], v157 offset:21504
	ds_read_b128 v[214:217], v157 offset:22528
	ds_read_b128 v[218:221], v157 offset:23552
	global_load_lds_dwordx4 v[150:151], off
	s_add_i32 m0, s70, 0x2000
	s_add_u32 s70, s40, 0x40000
	v_lshl_add_u64 v[222:223], s[40:41], 0, v[134:135]
	s_addc_u32 s71, s41, 0
	s_add_i32 s72, s52, s0
	global_load_lds_dwordx4 v[222:223], off
	v_lshl_add_u64 v[224:225], s[70:71], 0, v[130:131]
	s_mov_b32 m0, s72
	v_lshl_add_u64 v[226:227], s[64:65], 0, v[132:133]
	global_load_lds_dwordx4 v[224:225], off
	v_lshl_add_u64 v[224:225], s[70:71], 0, v[134:135]
	s_add_i32 m0, s72, 0x2000
	s_nop 0
	global_load_lds_dwordx4 v[224:225], off
	v_lshl_add_u64 v[224:225], s[64:65], 0, v[128:129]
	s_mov_b32 m0, s1
	s_nop 0
	global_load_lds_dwordx4 v[224:225], off
	s_mov_b32 m0, s14
	s_nop 0
	global_load_lds_dwordx4 v[226:227], off
	s_waitcnt vmcnt(8) lgkmcnt(0)
	s_barrier
	s_setprio 1
	v_mfma_f32_16x16x32_bf16 v[60:63], v[146:149], v[190:193], v[60:63]
	v_mfma_f32_16x16x32_bf16 v[56:59], v[166:169], v[190:193], v[56:59]
	v_mfma_f32_16x16x32_bf16 v[44:47], v[146:149], v[198:201], v[44:47]
	v_mfma_f32_16x16x32_bf16 v[40:43], v[166:169], v[198:201], v[40:43]
	v_mfma_f32_16x16x32_bf16 v[28:31], v[146:149], v[206:209], v[28:31]
	v_mfma_f32_16x16x32_bf16 v[24:27], v[166:169], v[206:209], v[24:27]
	v_mfma_f32_16x16x32_bf16 v[12:15], v[146:149], v[214:217], v[12:15]
	v_mfma_f32_16x16x32_bf16 v[8:11], v[166:169], v[214:217], v[8:11]
	v_mfma_f32_16x16x32_bf16 v[60:63], v[162:165], v[194:197], v[60:63]
	v_mfma_f32_16x16x32_bf16 v[56:59], v[170:173], v[194:197], v[56:59]
	v_mfma_f32_16x16x32_bf16 v[44:47], v[162:165], v[202:205], v[44:47]
	v_mfma_f32_16x16x32_bf16 v[40:43], v[170:173], v[202:205], v[40:43]
	v_mfma_f32_16x16x32_bf16 v[28:31], v[162:165], v[210:213], v[28:31]
	v_mfma_f32_16x16x32_bf16 v[24:27], v[170:173], v[210:213], v[24:27]
	v_mfma_f32_16x16x32_bf16 v[12:15], v[162:165], v[218:221], v[12:15]
	v_mfma_f32_16x16x32_bf16 v[8:11], v[170:173], v[218:221], v[8:11]
	v_mfma_f32_16x16x32_bf16 v[52:55], v[174:177], v[190:193], v[52:55]
	v_mfma_f32_16x16x32_bf16 v[48:51], v[182:185], v[190:193], v[48:51]
	v_mfma_f32_16x16x32_bf16 v[36:39], v[174:177], v[198:201], v[36:39]
	v_mfma_f32_16x16x32_bf16 v[32:35], v[182:185], v[198:201], v[32:35]
	v_mfma_f32_16x16x32_bf16 v[20:23], v[174:177], v[206:209], v[20:23]
	v_mfma_f32_16x16x32_bf16 v[16:19], v[182:185], v[206:209], v[16:19]
	v_mfma_f32_16x16x32_bf16 v[4:7], v[174:177], v[214:217], v[4:7]
	v_mfma_f32_16x16x32_bf16 v[0:3], v[182:185], v[214:217], v[0:3]
	v_mfma_f32_16x16x32_bf16 v[52:55], v[178:181], v[194:197], v[52:55]
	v_mfma_f32_16x16x32_bf16 v[48:51], v[186:189], v[194:197], v[48:51]
	v_mfma_f32_16x16x32_bf16 v[36:39], v[178:181], v[202:205], v[36:39]
	v_mfma_f32_16x16x32_bf16 v[32:35], v[186:189], v[202:205], v[32:35]
	v_mfma_f32_16x16x32_bf16 v[20:23], v[178:181], v[210:213], v[20:23]
	v_mfma_f32_16x16x32_bf16 v[16:19], v[186:189], v[210:213], v[16:19]
	v_mfma_f32_16x16x32_bf16 v[4:7], v[178:181], v[218:221], v[4:7]
	v_mfma_f32_16x16x32_bf16 v[0:3], v[186:189], v[218:221], v[0:3]
	s_setprio 0
	s_barrier
	s_add_i32 s70, 0, 0x18000
	v_add_u32_e32 v136, s70, v153
	s_add_i32 s71, 0, 0x1c000
	ds_read_b128 v[146:149], v136
	ds_read_b128 v[162:165], v136 offset:1024
	ds_read_b128 v[166:169], v136 offset:2048
	ds_read_b128 v[170:173], v136 offset:3072
	v_add_u32_e32 v136, s71, v153
	ds_read_b128 v[174:177], v136
	ds_read_b128 v[178:181], v136 offset:1024
	ds_read_b128 v[182:185], v136 offset:2048
	ds_read_b128 v[186:189], v136 offset:3072
	s_add_u32 s64, s64, 0x40000
	s_addc_u32 s65, s65, 0
	s_mov_b32 m0, s15
	v_lshl_add_u64 v[228:229], s[64:65], 0, v[128:129]
	ds_read_b128 v[190:193], v157 offset:32768
	ds_read_b128 v[194:197], v157 offset:33792
	ds_read_b128 v[198:201], v157 offset:34816
	ds_read_b128 v[202:205], v157 offset:35840
	ds_read_b128 v[206:209], v157 offset:36864
	ds_read_b128 v[210:213], v157 offset:37888
	ds_read_b128 v[214:217], v157 offset:38912
	ds_read_b128 v[218:221], v157 offset:39936
	global_load_lds_dwordx4 v[228:229], off
	v_lshl_add_u64 v[228:229], s[64:65], 0, v[132:133]
	s_mov_b32 m0, s33
	s_nop 0
	global_load_lds_dwordx4 v[228:229], off
	s_waitcnt vmcnt(8) lgkmcnt(0)
	s_barrier
	s_setprio 1
	v_mfma_f32_16x16x32_bf16 v[124:127], v[146:149], v[190:193], v[124:127]
	v_mfma_f32_16x16x32_bf16 v[120:123], v[166:169], v[190:193], v[120:123]
	v_mfma_f32_16x16x32_bf16 v[108:111], v[146:149], v[198:201], v[108:111]
	v_mfma_f32_16x16x32_bf16 v[104:107], v[166:169], v[198:201], v[104:107]
	v_mfma_f32_16x16x32_bf16 v[92:95], v[146:149], v[206:209], v[92:95]
	v_mfma_f32_16x16x32_bf16 v[88:91], v[166:169], v[206:209], v[88:91]
	v_mfma_f32_16x16x32_bf16 v[76:79], v[146:149], v[214:217], v[76:79]
	v_mfma_f32_16x16x32_bf16 v[72:75], v[166:169], v[214:217], v[72:75]
	v_mfma_f32_16x16x32_bf16 v[124:127], v[162:165], v[194:197], v[124:127]
	v_mfma_f32_16x16x32_bf16 v[120:123], v[170:173], v[194:197], v[120:123]
	v_mfma_f32_16x16x32_bf16 v[108:111], v[162:165], v[202:205], v[108:111]
	v_mfma_f32_16x16x32_bf16 v[104:107], v[170:173], v[202:205], v[104:107]
	v_mfma_f32_16x16x32_bf16 v[92:95], v[162:165], v[210:213], v[92:95]
	v_mfma_f32_16x16x32_bf16 v[88:91], v[170:173], v[210:213], v[88:91]
	v_mfma_f32_16x16x32_bf16 v[76:79], v[162:165], v[218:221], v[76:79]
	v_mfma_f32_16x16x32_bf16 v[72:75], v[170:173], v[218:221], v[72:75]
	v_mfma_f32_16x16x32_bf16 v[116:119], v[174:177], v[190:193], v[116:119]
	v_mfma_f32_16x16x32_bf16 v[112:115], v[182:185], v[190:193], v[112:115]
	v_mfma_f32_16x16x32_bf16 v[100:103], v[174:177], v[198:201], v[100:103]
	v_mfma_f32_16x16x32_bf16 v[96:99], v[182:185], v[198:201], v[96:99]
	v_mfma_f32_16x16x32_bf16 v[84:87], v[174:177], v[206:209], v[84:87]
	v_mfma_f32_16x16x32_bf16 v[80:83], v[182:185], v[206:209], v[80:83]
	v_mfma_f32_16x16x32_bf16 v[68:71], v[174:177], v[214:217], v[68:71]
	v_mfma_f32_16x16x32_bf16 v[64:67], v[182:185], v[214:217], v[64:67]
	v_mfma_f32_16x16x32_bf16 v[116:119], v[178:181], v[194:197], v[116:119]
	v_mfma_f32_16x16x32_bf16 v[112:115], v[186:189], v[194:197], v[112:115]
	v_mfma_f32_16x16x32_bf16 v[100:103], v[178:181], v[202:205], v[100:103]
	v_mfma_f32_16x16x32_bf16 v[96:99], v[186:189], v[202:205], v[96:99]
	v_mfma_f32_16x16x32_bf16 v[84:87], v[178:181], v[210:213], v[84:87]
	v_mfma_f32_16x16x32_bf16 v[80:83], v[186:189], v[210:213], v[80:83]
	v_mfma_f32_16x16x32_bf16 v[68:71], v[178:181], v[218:221], v[68:71]
	v_mfma_f32_16x16x32_bf16 v[64:67], v[186:189], v[218:221], v[64:67]
	s_setprio 0
	s_barrier
	s_add_i32 s64, s70, s0
	v_lshl_add_u64 v[150:151], v[150:151], 0, s[24:25]
	s_mov_b32 m0, s64
	ds_read_b128 v[190:193], v157 offset:49152
	ds_read_b128 v[194:197], v157 offset:50176
	ds_read_b128 v[198:201], v157 offset:51200
	ds_read_b128 v[202:205], v157 offset:52224
	ds_read_b128 v[206:209], v157 offset:53248
	ds_read_b128 v[210:213], v157 offset:54272
	ds_read_b128 v[214:217], v157 offset:55296
	ds_read_b128 v[218:221], v157 offset:56320
	global_load_lds_dwordx4 v[150:151], off
	s_add_i32 m0, s64, 0x2000
	s_add_u32 s40, s40, 0x40080
	v_lshl_add_u64 v[150:151], v[222:223], 0, s[24:25]
	s_addc_u32 s41, s41, 0
	s_add_i32 s64, s71, s0
	global_load_lds_dwordx4 v[150:151], off
	v_lshl_add_u64 v[150:151], s[40:41], 0, v[130:131]
	s_mov_b32 m0, s64
	s_nop 0
	global_load_lds_dwordx4 v[150:151], off
	v_lshl_add_u64 v[150:151], s[40:41], 0, v[134:135]
	s_add_i32 m0, s64, 0x2000
	s_nop 0
	global_load_lds_dwordx4 v[150:151], off
	v_lshl_add_u64 v[150:151], v[224:225], 0, s[24:25]
	s_mov_b32 m0, s42
	s_nop 0
	global_load_lds_dwordx4 v[150:151], off
	v_lshl_add_u64 v[150:151], v[226:227], 0, s[24:25]
	s_mov_b32 m0, s43
	s_nop 0
	global_load_lds_dwordx4 v[150:151], off
	s_waitcnt vmcnt(8) lgkmcnt(0)
	s_barrier
	s_setprio 1
	v_mfma_f32_16x16x32_bf16 v[60:63], v[146:149], v[190:193], v[60:63]
	v_mfma_f32_16x16x32_bf16 v[56:59], v[166:169], v[190:193], v[56:59]
	v_mfma_f32_16x16x32_bf16 v[44:47], v[146:149], v[198:201], v[44:47]
	v_mfma_f32_16x16x32_bf16 v[40:43], v[166:169], v[198:201], v[40:43]
	v_mfma_f32_16x16x32_bf16 v[28:31], v[146:149], v[206:209], v[28:31]
	v_mfma_f32_16x16x32_bf16 v[24:27], v[166:169], v[206:209], v[24:27]
	v_mfma_f32_16x16x32_bf16 v[12:15], v[146:149], v[214:217], v[12:15]
	v_mfma_f32_16x16x32_bf16 v[8:11], v[166:169], v[214:217], v[8:11]
	v_mfma_f32_16x16x32_bf16 v[60:63], v[162:165], v[194:197], v[60:63]
	v_mfma_f32_16x16x32_bf16 v[56:59], v[170:173], v[194:197], v[56:59]
	v_mfma_f32_16x16x32_bf16 v[44:47], v[162:165], v[202:205], v[44:47]
	v_mfma_f32_16x16x32_bf16 v[40:43], v[170:173], v[202:205], v[40:43]
	v_mfma_f32_16x16x32_bf16 v[28:31], v[162:165], v[210:213], v[28:31]
	v_mfma_f32_16x16x32_bf16 v[24:27], v[170:173], v[210:213], v[24:27]
	v_mfma_f32_16x16x32_bf16 v[12:15], v[162:165], v[218:221], v[12:15]
	v_mfma_f32_16x16x32_bf16 v[8:11], v[170:173], v[218:221], v[8:11]
	v_mfma_f32_16x16x32_bf16 v[52:55], v[174:177], v[190:193], v[52:55]
	v_mfma_f32_16x16x32_bf16 v[48:51], v[182:185], v[190:193], v[48:51]
	v_mfma_f32_16x16x32_bf16 v[36:39], v[174:177], v[198:201], v[36:39]
	v_mfma_f32_16x16x32_bf16 v[32:35], v[182:185], v[198:201], v[32:35]
	v_mfma_f32_16x16x32_bf16 v[20:23], v[174:177], v[206:209], v[20:23]
	v_mfma_f32_16x16x32_bf16 v[16:19], v[182:185], v[206:209], v[16:19]
	v_mfma_f32_16x16x32_bf16 v[4:7], v[174:177], v[214:217], v[4:7]
	v_mfma_f32_16x16x32_bf16 v[0:3], v[182:185], v[214:217], v[0:3]
	v_mfma_f32_16x16x32_bf16 v[52:55], v[178:181], v[194:197], v[52:55]
	v_mfma_f32_16x16x32_bf16 v[48:51], v[186:189], v[194:197], v[48:51]
	v_mfma_f32_16x16x32_bf16 v[36:39], v[178:181], v[202:205], v[36:39]
	v_mfma_f32_16x16x32_bf16 v[32:35], v[186:189], v[202:205], v[32:35]
	v_mfma_f32_16x16x32_bf16 v[20:23], v[178:181], v[210:213], v[20:23]
	v_mfma_f32_16x16x32_bf16 v[16:19], v[186:189], v[210:213], v[16:19]
	v_mfma_f32_16x16x32_bf16 v[4:7], v[178:181], v[218:221], v[4:7]
	v_mfma_f32_16x16x32_bf16 v[0:3], v[186:189], v[218:221], v[0:3]
	s_setprio 0
	s_barrier
	s_add_i32 s69, s69, 2
	s_add_u32 s38, s38, 0x100
	s_addc_u32 s39, s39, 0
	s_add_u32 s67, s67, 0x100
	s_addc_u32 s68, s68, 0
	s_cmp_gt_u32 s69, 13
	s_cbranch_scc0 .LBB0_649
	s_and_b64 vcc, exec, s[26:27]
	s_cbranch_vccz .LBB0_652
	s_barrier

.LBB0_769:
	ds_read_b128 v[154:157], v149
	ds_read_b128 v[162:165], v149 offset:1024
	ds_read_b128 v[166:169], v149 offset:2048
	ds_read_b128 v[170:173], v149 offset:3072
	ds_read_b128 v[174:177], v150
	ds_read_b128 v[178:181], v150 offset:1024
	ds_read_b128 v[182:185], v150 offset:2048
	ds_read_b128 v[186:189], v150 offset:3072
	s_add_u32 s30, s28, 0xfffc0080
	s_addc_u32 s31, s29, -1
	s_cmp_eq_u32 s54, 12
	s_cselect_b32 s37, s19, s31
	s_cselect_b32 s36, s49, s30
	s_cselect_b32 s31, s50, s53
	s_cselect_b32 s30, s51, s52
	v_lshl_add_u64 v[144:145], s[28:29], 0, v[136:137]
	s_add_i32 m0, s15, 0xc000
	ds_read_b128 v[190:193], v151
	ds_read_b128 v[194:197], v151 offset:1024
	ds_read_b128 v[198:201], v151 offset:2048
	ds_read_b128 v[202:205], v151 offset:3072
	ds_read_b128 v[206:209], v151 offset:4096
	ds_read_b128 v[210:213], v151 offset:5120
	ds_read_b128 v[214:217], v151 offset:6144
	ds_read_b128 v[218:221], v151 offset:7168
	global_load_lds_dwordx4 v[144:145], off
	v_lshl_add_u64 v[144:145], s[28:29], 0, v[138:139]
	s_add_i32 m0, s15, 0xe000
	s_nop 0
	global_load_lds_dwordx4 v[144:145], off
	s_waitcnt vmcnt(8) lgkmcnt(0)
	s_barrier
	s_setprio 1
	v_mfma_f32_16x16x32_bf16 v[124:127], v[154:157], v[190:193], v[124:127]
	v_mfma_f32_16x16x32_bf16 v[120:123], v[166:169], v[190:193], v[120:123]
	v_mfma_f32_16x16x32_bf16 v[108:111], v[154:157], v[198:201], v[108:111]
	v_mfma_f32_16x16x32_bf16 v[104:107], v[166:169], v[198:201], v[104:107]
	v_mfma_f32_16x16x32_bf16 v[92:95], v[154:157], v[206:209], v[92:95]
	v_mfma_f32_16x16x32_bf16 v[88:91], v[166:169], v[206:209], v[88:91]
	v_mfma_f32_16x16x32_bf16 v[76:79], v[154:157], v[214:217], v[76:79]
	v_mfma_f32_16x16x32_bf16 v[72:75], v[166:169], v[214:217], v[72:75]
	v_mfma_f32_16x16x32_bf16 v[124:127], v[162:165], v[194:197], v[124:127]
	v_mfma_f32_16x16x32_bf16 v[120:123], v[170:173], v[194:197], v[120:123]
	v_mfma_f32_16x16x32_bf16 v[108:111], v[162:165], v[202:205], v[108:111]
	v_mfma_f32_16x16x32_bf16 v[104:107], v[170:173], v[202:205], v[104:107]
	v_mfma_f32_16x16x32_bf16 v[92:95], v[162:165], v[210:213], v[92:95]
	v_mfma_f32_16x16x32_bf16 v[88:91], v[170:173], v[210:213], v[88:91]
	v_mfma_f32_16x16x32_bf16 v[76:79], v[162:165], v[218:221], v[76:79]
	v_mfma_f32_16x16x32_bf16 v[72:75], v[170:173], v[218:221], v[72:75]
	v_mfma_f32_16x16x32_bf16 v[116:119], v[174:177], v[190:193], v[116:119]
	v_mfma_f32_16x16x32_bf16 v[112:115], v[182:185], v[190:193], v[112:115]
	v_mfma_f32_16x16x32_bf16 v[100:103], v[174:177], v[198:201], v[100:103]
	v_mfma_f32_16x16x32_bf16 v[96:99], v[182:185], v[198:201], v[96:99]
	v_mfma_f32_16x16x32_bf16 v[84:87], v[174:177], v[206:209], v[84:87]
	v_mfma_f32_16x16x32_bf16 v[80:83], v[182:185], v[206:209], v[80:83]
	v_mfma_f32_16x16x32_bf16 v[68:71], v[174:177], v[214:217], v[68:71]
	v_mfma_f32_16x16x32_bf16 v[64:67], v[182:185], v[214:217], v[64:67]
	v_mfma_f32_16x16x32_bf16 v[116:119], v[178:181], v[194:197], v[116:119]
	v_mfma_f32_16x16x32_bf16 v[112:115], v[186:189], v[194:197], v[112:115]
	v_mfma_f32_16x16x32_bf16 v[100:103], v[178:181], v[202:205], v[100:103]
	v_mfma_f32_16x16x32_bf16 v[96:99], v[186:189], v[202:205], v[96:99]
	v_mfma_f32_16x16x32_bf16 v[84:87], v[178:181], v[210:213], v[84:87]
	v_mfma_f32_16x16x32_bf16 v[80:83], v[186:189], v[210:213], v[80:83]
	v_mfma_f32_16x16x32_bf16 v[68:71], v[178:181], v[218:221], v[68:71]
	v_mfma_f32_16x16x32_bf16 v[64:67], v[186:189], v[218:221], v[64:67]
	s_setprio 0
	s_barrier
	s_add_i32 s55, s42, s0
	v_lshl_add_u64 v[144:145], s[30:31], 0, v[132:133]
	s_mov_b32 m0, s55
	ds_read_b128 v[190:193], v151 offset:16384
	ds_read_b128 v[194:197], v151 offset:17408
	ds_read_b128 v[198:201], v151 offset:18432
	ds_read_b128 v[202:205], v151 offset:19456
	ds_read_b128 v[206:209], v151 offset:20480
	ds_read_b128 v[210:213], v151 offset:21504
	ds_read_b128 v[214:217], v151 offset:22528
	ds_read_b128 v[218:221], v151 offset:23552
	global_load_lds_dwordx4 v[144:145], off
	s_add_i32 m0, s55, 0x2000
	s_add_u32 s56, s30, 0x40000
	v_lshl_add_u64 v[158:159], s[30:31], 0, v[128:129]
	s_addc_u32 s57, s31, 0
	s_add_i32 s55, s43, s0
	global_load_lds_dwordx4 v[158:159], off
	v_lshl_add_u64 v[222:223], s[56:57], 0, v[132:133]
	s_mov_b32 m0, s55
	v_lshl_add_u64 v[224:225], s[36:37], 0, v[130:131]
	global_load_lds_dwordx4 v[222:223], off
	v_lshl_add_u64 v[222:223], s[56:57], 0, v[128:129]
	s_add_i32 m0, s55, 0x2000
	s_nop 0
	global_load_lds_dwordx4 v[222:223], off
	v_lshl_add_u64 v[222:223], s[36:37], 0, v[134:135]
	s_mov_b32 m0, s15
	s_nop 0
	global_load_lds_dwordx4 v[222:223], off
	s_mov_b32 m0, s27
	s_nop 0
	global_load_lds_dwordx4 v[224:225], off
	s_waitcnt vmcnt(8) lgkmcnt(0)
	s_barrier
	s_setprio 1
	v_mfma_f32_16x16x32_bf16 v[60:63], v[154:157], v[190:193], v[60:63]
	v_mfma_f32_16x16x32_bf16 v[56:59], v[166:169], v[190:193], v[56:59]
	v_mfma_f32_16x16x32_bf16 v[44:47], v[154:157], v[198:201], v[44:47]
	v_mfma_f32_16x16x32_bf16 v[40:43], v[166:169], v[198:201], v[40:43]
	v_mfma_f32_16x16x32_bf16 v[28:31], v[154:157], v[206:209], v[28:31]
	v_mfma_f32_16x16x32_bf16 v[24:27], v[166:169], v[206:209], v[24:27]
	v_mfma_f32_16x16x32_bf16 v[12:15], v[154:157], v[214:217], v[12:15]
	v_mfma_f32_16x16x32_bf16 v[8:11], v[166:169], v[214:217], v[8:11]
	v_mfma_f32_16x16x32_bf16 v[60:63], v[162:165], v[194:197], v[60:63]
	v_mfma_f32_16x16x32_bf16 v[56:59], v[170:173], v[194:197], v[56:59]
	v_mfma_f32_16x16x32_bf16 v[44:47], v[162:165], v[202:205], v[44:47]
	v_mfma_f32_16x16x32_bf16 v[40:43], v[170:173], v[202:205], v[40:43]
	v_mfma_f32_16x16x32_bf16 v[28:31], v[162:165], v[210:213], v[28:31]
	v_mfma_f32_16x16x32_bf16 v[24:27], v[170:173], v[210:213], v[24:27]
	v_mfma_f32_16x16x32_bf16 v[12:15], v[162:165], v[218:221], v[12:15]
	v_mfma_f32_16x16x32_bf16 v[8:11], v[170:173], v[218:221], v[8:11]
	v_mfma_f32_16x16x32_bf16 v[52:55], v[174:177], v[190:193], v[52:55]
	v_mfma_f32_16x16x32_bf16 v[48:51], v[182:185], v[190:193], v[48:51]
	v_mfma_f32_16x16x32_bf16 v[36:39], v[174:177], v[198:201], v[36:39]
	v_mfma_f32_16x16x32_bf16 v[32:35], v[182:185], v[198:201], v[32:35]
	v_mfma_f32_16x16x32_bf16 v[20:23], v[174:177], v[206:209], v[20:23]
	v_mfma_f32_16x16x32_bf16 v[16:19], v[182:185], v[206:209], v[16:19]
	v_mfma_f32_16x16x32_bf16 v[4:7], v[174:177], v[214:217], v[4:7]
	v_mfma_f32_16x16x32_bf16 v[0:3], v[182:185], v[214:217], v[0:3]
	v_mfma_f32_16x16x32_bf16 v[52:55], v[178:181], v[194:197], v[52:55]
	v_mfma_f32_16x16x32_bf16 v[48:51], v[186:189], v[194:197], v[48:51]
	v_mfma_f32_16x16x32_bf16 v[36:39], v[178:181], v[202:205], v[36:39]
	v_mfma_f32_16x16x32_bf16 v[32:35], v[186:189], v[202:205], v[32:35]
	v_mfma_f32_16x16x32_bf16 v[20:23], v[178:181], v[210:213], v[20:23]
	v_mfma_f32_16x16x32_bf16 v[16:19], v[186:189], v[210:213], v[16:19]
	v_mfma_f32_16x16x32_bf16 v[4:7], v[178:181], v[218:221], v[4:7]
	v_mfma_f32_16x16x32_bf16 v[0:3], v[186:189], v[218:221], v[0:3]
	s_setprio 0
	s_barrier
	s_add_i32 s55, 0, 0x18000
	v_add_u32_e32 v153, s55, v147
	s_add_i32 s56, 0, 0x1c000
	ds_read_b128 v[154:157], v153
	ds_read_b128 v[162:165], v153 offset:1024
	ds_read_b128 v[166:169], v153 offset:2048
	ds_read_b128 v[170:173], v153 offset:3072
	v_add_u32_e32 v153, s56, v147
	ds_read_b128 v[174:177], v153
	ds_read_b128 v[178:181], v153 offset:1024
	ds_read_b128 v[182:185], v153 offset:2048
	ds_read_b128 v[186:189], v153 offset:3072
	s_add_u32 s36, s36, 0x40000
	s_addc_u32 s37, s37, 0
	s_mov_b32 m0, s33
	v_lshl_add_u64 v[226:227], s[36:37], 0, v[134:135]
	ds_read_b128 v[190:193], v151 offset:32768
	ds_read_b128 v[194:197], v151 offset:33792
	ds_read_b128 v[198:201], v151 offset:34816
	ds_read_b128 v[202:205], v151 offset:35840
	ds_read_b128 v[206:209], v151 offset:36864
	ds_read_b128 v[210:213], v151 offset:37888
	ds_read_b128 v[214:217], v151 offset:38912
	ds_read_b128 v[218:221], v151 offset:39936
	global_load_lds_dwordx4 v[226:227], off
	v_lshl_add_u64 v[226:227], s[36:37], 0, v[130:131]
	s_mov_b32 m0, s35
	s_nop 0
	global_load_lds_dwordx4 v[226:227], off
	s_waitcnt vmcnt(8) lgkmcnt(0)
	s_barrier
	s_setprio 1
	v_mfma_f32_16x16x32_bf16 v[124:127], v[154:157], v[190:193], v[124:127]
	v_mfma_f32_16x16x32_bf16 v[120:123], v[166:169], v[190:193], v[120:123]
	v_mfma_f32_16x16x32_bf16 v[108:111], v[154:157], v[198:201], v[108:111]
	v_mfma_f32_16x16x32_bf16 v[104:107], v[166:169], v[198:201], v[104:107]
	v_mfma_f32_16x16x32_bf16 v[92:95], v[154:157], v[206:209], v[92:95]
	v_mfma_f32_16x16x32_bf16 v[88:91], v[166:169], v[206:209], v[88:91]
	v_mfma_f32_16x16x32_bf16 v[76:79], v[154:157], v[214:217], v[76:79]
	v_mfma_f32_16x16x32_bf16 v[72:75], v[166:169], v[214:217], v[72:75]
	v_mfma_f32_16x16x32_bf16 v[124:127], v[162:165], v[194:197], v[124:127]
	v_mfma_f32_16x16x32_bf16 v[120:123], v[170:173], v[194:197], v[120:123]
	v_mfma_f32_16x16x32_bf16 v[108:111], v[162:165], v[202:205], v[108:111]
	v_mfma_f32_16x16x32_bf16 v[104:107], v[170:173], v[202:205], v[104:107]
	v_mfma_f32_16x16x32_bf16 v[92:95], v[162:165], v[210:213], v[92:95]
	v_mfma_f32_16x16x32_bf16 v[88:91], v[170:173], v[210:213], v[88:91]
	v_mfma_f32_16x16x32_bf16 v[76:79], v[162:165], v[218:221], v[76:79]
	v_mfma_f32_16x16x32_bf16 v[72:75], v[170:173], v[218:221], v[72:75]
	v_mfma_f32_16x16x32_bf16 v[116:119], v[174:177], v[190:193], v[116:119]
	v_mfma_f32_16x16x32_bf16 v[112:115], v[182:185], v[190:193], v[112:115]
	v_mfma_f32_16x16x32_bf16 v[100:103], v[174:177], v[198:201], v[100:103]
	v_mfma_f32_16x16x32_bf16 v[96:99], v[182:185], v[198:201], v[96:99]
	v_mfma_f32_16x16x32_bf16 v[84:87], v[174:177], v[206:209], v[84:87]
	v_mfma_f32_16x16x32_bf16 v[80:83], v[182:185], v[206:209], v[80:83]
	v_mfma_f32_16x16x32_bf16 v[68:71], v[174:177], v[214:217], v[68:71]
	v_mfma_f32_16x16x32_bf16 v[64:67], v[182:185], v[214:217], v[64:67]
	v_mfma_f32_16x16x32_bf16 v[116:119], v[178:181], v[194:197], v[116:119]
	v_mfma_f32_16x16x32_bf16 v[112:115], v[186:189], v[194:197], v[112:115]
	v_mfma_f32_16x16x32_bf16 v[100:103], v[178:181], v[202:205], v[100:103]
	v_mfma_f32_16x16x32_bf16 v[96:99], v[186:189], v[202:205], v[96:99]
	v_mfma_f32_16x16x32_bf16 v[84:87], v[178:181], v[210:213], v[84:87]
	v_mfma_f32_16x16x32_bf16 v[80:83], v[186:189], v[210:213], v[80:83]
	v_mfma_f32_16x16x32_bf16 v[68:71], v[178:181], v[218:221], v[68:71]
	v_mfma_f32_16x16x32_bf16 v[64:67], v[186:189], v[218:221], v[64:67]
	s_setprio 0
	s_barrier
	s_add_i32 s36, s55, s0
	v_lshl_add_u64 v[144:145], v[144:145], 0, s[12:13]
	s_mov_b32 m0, s36
	ds_read_b128 v[190:193], v151 offset:49152
	ds_read_b128 v[194:197], v151 offset:50176
	ds_read_b128 v[198:201], v151 offset:51200
	ds_read_b128 v[202:205], v151 offset:52224
	ds_read_b128 v[206:209], v151 offset:53248
	ds_read_b128 v[210:213], v151 offset:54272
	ds_read_b128 v[214:217], v151 offset:55296
	ds_read_b128 v[218:221], v151 offset:56320
	global_load_lds_dwordx4 v[144:145], off
	s_add_i32 m0, s36, 0x2000
	s_add_u32 s30, s30, 0x40080
	v_lshl_add_u64 v[144:145], v[158:159], 0, s[12:13]
	s_addc_u32 s31, s31, 0
	s_add_i32 s36, s56, s0
	global_load_lds_dwordx4 v[144:145], off
	v_lshl_add_u64 v[144:145], s[30:31], 0, v[132:133]
	s_mov_b32 m0, s36
	s_nop 0
	global_load_lds_dwordx4 v[144:145], off
	v_lshl_add_u64 v[144:145], s[30:31], 0, v[128:129]
	s_add_i32 m0, s36, 0x2000
	s_nop 0
	global_load_lds_dwordx4 v[144:145], off
	v_lshl_add_u64 v[144:145], v[222:223], 0, s[12:13]
	s_mov_b32 m0, s39
	s_nop 0
	global_load_lds_dwordx4 v[144:145], off
	v_lshl_add_u64 v[144:145], v[224:225], 0, s[12:13]
	s_mov_b32 m0, s40
	s_nop 0
	global_load_lds_dwordx4 v[144:145], off
	s_waitcnt vmcnt(8) lgkmcnt(0)
	s_barrier
	s_setprio 1
	v_mfma_f32_16x16x32_bf16 v[60:63], v[154:157], v[190:193], v[60:63]
	v_mfma_f32_16x16x32_bf16 v[56:59], v[166:169], v[190:193], v[56:59]
	v_mfma_f32_16x16x32_bf16 v[44:47], v[154:157], v[198:201], v[44:47]
	v_mfma_f32_16x16x32_bf16 v[40:43], v[166:169], v[198:201], v[40:43]
	v_mfma_f32_16x16x32_bf16 v[28:31], v[154:157], v[206:209], v[28:31]
	v_mfma_f32_16x16x32_bf16 v[24:27], v[166:169], v[206:209], v[24:27]
	v_mfma_f32_16x16x32_bf16 v[12:15], v[154:157], v[214:217], v[12:15]
	v_mfma_f32_16x16x32_bf16 v[8:11], v[166:169], v[214:217], v[8:11]
	v_mfma_f32_16x16x32_bf16 v[60:63], v[162:165], v[194:197], v[60:63]
	v_mfma_f32_16x16x32_bf16 v[56:59], v[170:173], v[194:197], v[56:59]
	v_mfma_f32_16x16x32_bf16 v[44:47], v[162:165], v[202:205], v[44:47]
	v_mfma_f32_16x16x32_bf16 v[40:43], v[170:173], v[202:205], v[40:43]
	v_mfma_f32_16x16x32_bf16 v[28:31], v[162:165], v[210:213], v[28:31]
	v_mfma_f32_16x16x32_bf16 v[24:27], v[170:173], v[210:213], v[24:27]
	v_mfma_f32_16x16x32_bf16 v[12:15], v[162:165], v[218:221], v[12:15]
	v_mfma_f32_16x16x32_bf16 v[8:11], v[170:173], v[218:221], v[8:11]
	v_mfma_f32_16x16x32_bf16 v[52:55], v[174:177], v[190:193], v[52:55]
	v_mfma_f32_16x16x32_bf16 v[48:51], v[182:185], v[190:193], v[48:51]
	v_mfma_f32_16x16x32_bf16 v[36:39], v[174:177], v[198:201], v[36:39]
	v_mfma_f32_16x16x32_bf16 v[32:35], v[182:185], v[198:201], v[32:35]
	v_mfma_f32_16x16x32_bf16 v[20:23], v[174:177], v[206:209], v[20:23]
	v_mfma_f32_16x16x32_bf16 v[16:19], v[182:185], v[206:209], v[16:19]
	v_mfma_f32_16x16x32_bf16 v[4:7], v[174:177], v[214:217], v[4:7]
	v_mfma_f32_16x16x32_bf16 v[0:3], v[182:185], v[214:217], v[0:3]
	v_mfma_f32_16x16x32_bf16 v[52:55], v[178:181], v[194:197], v[52:55]
	v_mfma_f32_16x16x32_bf16 v[48:51], v[186:189], v[194:197], v[48:51]
	v_mfma_f32_16x16x32_bf16 v[36:39], v[178:181], v[202:205], v[36:39]
	v_mfma_f32_16x16x32_bf16 v[32:35], v[186:189], v[202:205], v[32:35]
	v_mfma_f32_16x16x32_bf16 v[20:23], v[178:181], v[210:213], v[20:23]
	v_mfma_f32_16x16x32_bf16 v[16:19], v[186:189], v[210:213], v[16:19]
	v_mfma_f32_16x16x32_bf16 v[4:7], v[178:181], v[218:221], v[4:7]
	v_mfma_f32_16x16x32_bf16 v[0:3], v[186:189], v[218:221], v[0:3]
	s_setprio 0
	s_barrier
	s_add_i32 s54, s54, 2
	s_add_u32 s28, s28, 0x100
	s_addc_u32 s29, s29, 0
	s_add_u32 s52, s52, 0x100
	s_addc_u32 s53, s53, 0
	s_cmp_gt_u32 s54, 13
	s_cbranch_scc0 .LBB0_769
	s_and_b64 vcc, exec, s[16:17]
	s_cbranch_vccz .LBB0_772
	s_barrier

.LBB0_842:
	ds_read_b128 v[144:147], v151
	ds_read_b128 v[156:159], v151 offset:1024
	ds_read_b128 v[162:165], v151 offset:2048
	ds_read_b128 v[166:169], v151 offset:3072
	ds_read_b128 v[170:173], v152
	ds_read_b128 v[174:177], v152 offset:1024
	ds_read_b128 v[178:181], v152 offset:2048
	ds_read_b128 v[182:185], v152 offset:3072
	s_add_u32 s36, s30, 0xfff00080
	s_addc_u32 s37, s31, -1
	s_cmp_eq_u32 s60, 60
	s_cselect_b32 s39, s25, s37
	s_cselect_b32 s38, s53, s36
	s_cselect_b32 s37, s54, s57
	s_cselect_b32 s36, s55, s56
	v_lshl_add_u64 v[218:219], s[30:31], 0, v[136:137]
	s_add_i32 m0, s1, 0xc000
	ds_read_b128 v[186:189], v153
	ds_read_b128 v[190:193], v153 offset:1024
	ds_read_b128 v[194:197], v153 offset:2048
	ds_read_b128 v[198:201], v153 offset:3072
	ds_read_b128 v[202:205], v153 offset:4096
	ds_read_b128 v[206:209], v153 offset:5120
	ds_read_b128 v[210:213], v153 offset:6144
	ds_read_b128 v[214:217], v153 offset:7168
	global_load_lds_dwordx4 v[218:219], off
	v_lshl_add_u64 v[218:219], s[30:31], 0, v[138:139]
	s_add_i32 m0, s1, 0xe000
	s_nop 0
	global_load_lds_dwordx4 v[218:219], off
	s_waitcnt vmcnt(8) lgkmcnt(0)
	s_barrier
	s_setprio 1
	v_mfma_f32_16x16x32_bf16 v[124:127], v[144:147], v[186:189], v[124:127]
	v_mfma_f32_16x16x32_bf16 v[120:123], v[162:165], v[186:189], v[120:123]
	v_mfma_f32_16x16x32_bf16 v[108:111], v[144:147], v[194:197], v[108:111]
	v_mfma_f32_16x16x32_bf16 v[104:107], v[162:165], v[194:197], v[104:107]
	v_mfma_f32_16x16x32_bf16 v[92:95], v[144:147], v[202:205], v[92:95]
	v_mfma_f32_16x16x32_bf16 v[88:91], v[162:165], v[202:205], v[88:91]
	v_mfma_f32_16x16x32_bf16 v[76:79], v[144:147], v[210:213], v[76:79]
	v_mfma_f32_16x16x32_bf16 v[72:75], v[162:165], v[210:213], v[72:75]
	v_mfma_f32_16x16x32_bf16 v[124:127], v[156:159], v[190:193], v[124:127]
	v_mfma_f32_16x16x32_bf16 v[120:123], v[166:169], v[190:193], v[120:123]
	v_mfma_f32_16x16x32_bf16 v[108:111], v[156:159], v[198:201], v[108:111]
	v_mfma_f32_16x16x32_bf16 v[104:107], v[166:169], v[198:201], v[104:107]
	v_mfma_f32_16x16x32_bf16 v[92:95], v[156:159], v[206:209], v[92:95]
	v_mfma_f32_16x16x32_bf16 v[88:91], v[166:169], v[206:209], v[88:91]
	v_mfma_f32_16x16x32_bf16 v[76:79], v[156:159], v[214:217], v[76:79]
	v_mfma_f32_16x16x32_bf16 v[72:75], v[166:169], v[214:217], v[72:75]
	v_mfma_f32_16x16x32_bf16 v[116:119], v[170:173], v[186:189], v[116:119]
	v_mfma_f32_16x16x32_bf16 v[112:115], v[178:181], v[186:189], v[112:115]
	v_mfma_f32_16x16x32_bf16 v[100:103], v[170:173], v[194:197], v[100:103]
	v_mfma_f32_16x16x32_bf16 v[96:99], v[178:181], v[194:197], v[96:99]
	v_mfma_f32_16x16x32_bf16 v[84:87], v[170:173], v[202:205], v[84:87]
	v_mfma_f32_16x16x32_bf16 v[80:83], v[178:181], v[202:205], v[80:83]
	v_mfma_f32_16x16x32_bf16 v[68:71], v[170:173], v[210:213], v[68:71]
	v_mfma_f32_16x16x32_bf16 v[64:67], v[178:181], v[210:213], v[64:67]
	v_mfma_f32_16x16x32_bf16 v[116:119], v[174:177], v[190:193], v[116:119]
	v_mfma_f32_16x16x32_bf16 v[112:115], v[182:185], v[190:193], v[112:115]
	v_mfma_f32_16x16x32_bf16 v[100:103], v[174:177], v[198:201], v[100:103]
	v_mfma_f32_16x16x32_bf16 v[96:99], v[182:185], v[198:201], v[96:99]
	v_mfma_f32_16x16x32_bf16 v[84:87], v[174:177], v[206:209], v[84:87]
	v_mfma_f32_16x16x32_bf16 v[80:83], v[182:185], v[206:209], v[80:83]
	v_mfma_f32_16x16x32_bf16 v[68:71], v[174:177], v[214:217], v[68:71]
	v_mfma_f32_16x16x32_bf16 v[64:67], v[182:185], v[214:217], v[64:67]
	s_setprio 0
	s_barrier
	s_add_i32 s61, s49, s0
	v_lshl_add_u64 v[218:219], s[36:37], 0, v[130:131]
	s_mov_b32 m0, s61
	ds_read_b128 v[186:189], v153 offset:16384
	ds_read_b128 v[190:193], v153 offset:17408
	ds_read_b128 v[194:197], v153 offset:18432
	ds_read_b128 v[198:201], v153 offset:19456
	ds_read_b128 v[202:205], v153 offset:20480
	ds_read_b128 v[206:209], v153 offset:21504
	ds_read_b128 v[210:213], v153 offset:22528
	ds_read_b128 v[214:217], v153 offset:23552
	global_load_lds_dwordx4 v[218:219], off
	s_add_i32 m0, s61, 0x2000
	s_add_u32 s62, s36, 0x100000
	v_lshl_add_u64 v[220:221], s[36:37], 0, v[134:135]
	s_addc_u32 s63, s37, 0
	s_add_i32 s61, s50, s0
	global_load_lds_dwordx4 v[220:221], off
	v_lshl_add_u64 v[222:223], s[62:63], 0, v[130:131]
	s_mov_b32 m0, s61
	v_lshl_add_u64 v[224:225], s[38:39], 0, v[132:133]
	global_load_lds_dwordx4 v[222:223], off
	v_lshl_add_u64 v[222:223], s[62:63], 0, v[134:135]
	s_add_i32 m0, s61, 0x2000
	s_nop 0
	global_load_lds_dwordx4 v[222:223], off
	v_lshl_add_u64 v[222:223], s[38:39], 0, v[128:129]
	s_mov_b32 m0, s1
	s_nop 0
	global_load_lds_dwordx4 v[222:223], off
	s_mov_b32 m0, s14
	s_nop 0
	global_load_lds_dwordx4 v[224:225], off
	s_waitcnt vmcnt(8) lgkmcnt(0)
	s_barrier
	s_setprio 1
	v_mfma_f32_16x16x32_bf16 v[60:63], v[144:147], v[186:189], v[60:63]
	v_mfma_f32_16x16x32_bf16 v[56:59], v[162:165], v[186:189], v[56:59]
	v_mfma_f32_16x16x32_bf16 v[44:47], v[144:147], v[194:197], v[44:47]
	v_mfma_f32_16x16x32_bf16 v[40:43], v[162:165], v[194:197], v[40:43]
	v_mfma_f32_16x16x32_bf16 v[28:31], v[144:147], v[202:205], v[28:31]
	v_mfma_f32_16x16x32_bf16 v[24:27], v[162:165], v[202:205], v[24:27]
	v_mfma_f32_16x16x32_bf16 v[12:15], v[144:147], v[210:213], v[12:15]
	v_mfma_f32_16x16x32_bf16 v[8:11], v[162:165], v[210:213], v[8:11]
	v_mfma_f32_16x16x32_bf16 v[60:63], v[156:159], v[190:193], v[60:63]
	v_mfma_f32_16x16x32_bf16 v[56:59], v[166:169], v[190:193], v[56:59]
	v_mfma_f32_16x16x32_bf16 v[44:47], v[156:159], v[198:201], v[44:47]
	v_mfma_f32_16x16x32_bf16 v[40:43], v[166:169], v[198:201], v[40:43]
	v_mfma_f32_16x16x32_bf16 v[28:31], v[156:159], v[206:209], v[28:31]
	v_mfma_f32_16x16x32_bf16 v[24:27], v[166:169], v[206:209], v[24:27]
	v_mfma_f32_16x16x32_bf16 v[12:15], v[156:159], v[214:217], v[12:15]
	v_mfma_f32_16x16x32_bf16 v[8:11], v[166:169], v[214:217], v[8:11]
	v_mfma_f32_16x16x32_bf16 v[52:55], v[170:173], v[186:189], v[52:55]
	v_mfma_f32_16x16x32_bf16 v[48:51], v[178:181], v[186:189], v[48:51]
	v_mfma_f32_16x16x32_bf16 v[36:39], v[170:173], v[194:197], v[36:39]
	v_mfma_f32_16x16x32_bf16 v[32:35], v[178:181], v[194:197], v[32:35]
	v_mfma_f32_16x16x32_bf16 v[20:23], v[170:173], v[202:205], v[20:23]
	v_mfma_f32_16x16x32_bf16 v[16:19], v[178:181], v[202:205], v[16:19]
	v_mfma_f32_16x16x32_bf16 v[4:7], v[170:173], v[210:213], v[4:7]
	v_mfma_f32_16x16x32_bf16 v[0:3], v[178:181], v[210:213], v[0:3]
	v_mfma_f32_16x16x32_bf16 v[52:55], v[174:177], v[190:193], v[52:55]
	v_mfma_f32_16x16x32_bf16 v[48:51], v[182:185], v[190:193], v[48:51]
	v_mfma_f32_16x16x32_bf16 v[36:39], v[174:177], v[198:201], v[36:39]
	v_mfma_f32_16x16x32_bf16 v[32:35], v[182:185], v[198:201], v[32:35]
	v_mfma_f32_16x16x32_bf16 v[20:23], v[174:177], v[206:209], v[20:23]
	v_mfma_f32_16x16x32_bf16 v[16:19], v[182:185], v[206:209], v[16:19]
	v_mfma_f32_16x16x32_bf16 v[4:7], v[174:177], v[214:217], v[4:7]
	v_mfma_f32_16x16x32_bf16 v[0:3], v[182:185], v[214:217], v[0:3]
	s_setprio 0
	s_barrier
	s_add_i32 s61, 0, 0x18000
	v_add_u32_e32 v155, s61, v149
	s_add_i32 s62, 0, 0x1c000
	ds_read_b128 v[144:147], v155
	ds_read_b128 v[156:159], v155 offset:1024
	ds_read_b128 v[162:165], v155 offset:2048
	ds_read_b128 v[166:169], v155 offset:3072
	v_add_u32_e32 v155, s62, v149
	ds_read_b128 v[170:173], v155
	ds_read_b128 v[174:177], v155 offset:1024
	ds_read_b128 v[178:181], v155 offset:2048
	ds_read_b128 v[182:185], v155 offset:3072
	s_add_u32 s38, s38, 0x100000
	s_addc_u32 s39, s39, 0
	s_mov_b32 m0, s15
	v_lshl_add_u64 v[226:227], s[38:39], 0, v[128:129]
	ds_read_b128 v[186:189], v153 offset:32768
	ds_read_b128 v[190:193], v153 offset:33792
	ds_read_b128 v[194:197], v153 offset:34816
	ds_read_b128 v[198:201], v153 offset:35840
	ds_read_b128 v[202:205], v153 offset:36864
	ds_read_b128 v[206:209], v153 offset:37888
	ds_read_b128 v[210:213], v153 offset:38912
	ds_read_b128 v[214:217], v153 offset:39936
	global_load_lds_dwordx4 v[226:227], off
	v_lshl_add_u64 v[226:227], s[38:39], 0, v[132:133]
	s_mov_b32 m0, s33
	s_nop 0
	global_load_lds_dwordx4 v[226:227], off
	s_waitcnt vmcnt(8) lgkmcnt(0)
	s_barrier
	s_setprio 1
	v_mfma_f32_16x16x32_bf16 v[124:127], v[144:147], v[186:189], v[124:127]
	v_mfma_f32_16x16x32_bf16 v[120:123], v[162:165], v[186:189], v[120:123]
	v_mfma_f32_16x16x32_bf16 v[108:111], v[144:147], v[194:197], v[108:111]
	v_mfma_f32_16x16x32_bf16 v[104:107], v[162:165], v[194:197], v[104:107]
	v_mfma_f32_16x16x32_bf16 v[92:95], v[144:147], v[202:205], v[92:95]
	v_mfma_f32_16x16x32_bf16 v[88:91], v[162:165], v[202:205], v[88:91]
	v_mfma_f32_16x16x32_bf16 v[76:79], v[144:147], v[210:213], v[76:79]
	v_mfma_f32_16x16x32_bf16 v[72:75], v[162:165], v[210:213], v[72:75]
	v_mfma_f32_16x16x32_bf16 v[124:127], v[156:159], v[190:193], v[124:127]
	v_mfma_f32_16x16x32_bf16 v[120:123], v[166:169], v[190:193], v[120:123]
	v_mfma_f32_16x16x32_bf16 v[108:111], v[156:159], v[198:201], v[108:111]
	v_mfma_f32_16x16x32_bf16 v[104:107], v[166:169], v[198:201], v[104:107]
	v_mfma_f32_16x16x32_bf16 v[92:95], v[156:159], v[206:209], v[92:95]
	v_mfma_f32_16x16x32_bf16 v[88:91], v[166:169], v[206:209], v[88:91]
	v_mfma_f32_16x16x32_bf16 v[76:79], v[156:159], v[214:217], v[76:79]
	v_mfma_f32_16x16x32_bf16 v[72:75], v[166:169], v[214:217], v[72:75]
	v_mfma_f32_16x16x32_bf16 v[116:119], v[170:173], v[186:189], v[116:119]
	v_mfma_f32_16x16x32_bf16 v[112:115], v[178:181], v[186:189], v[112:115]
	v_mfma_f32_16x16x32_bf16 v[100:103], v[170:173], v[194:197], v[100:103]
	v_mfma_f32_16x16x32_bf16 v[96:99], v[178:181], v[194:197], v[96:99]
	v_mfma_f32_16x16x32_bf16 v[84:87], v[170:173], v[202:205], v[84:87]
	v_mfma_f32_16x16x32_bf16 v[80:83], v[178:181], v[202:205], v[80:83]
	v_mfma_f32_16x16x32_bf16 v[68:71], v[170:173], v[210:213], v[68:71]
	v_mfma_f32_16x16x32_bf16 v[64:67], v[178:181], v[210:213], v[64:67]
	v_mfma_f32_16x16x32_bf16 v[116:119], v[174:177], v[190:193], v[116:119]
	v_mfma_f32_16x16x32_bf16 v[112:115], v[182:185], v[190:193], v[112:115]
	v_mfma_f32_16x16x32_bf16 v[100:103], v[174:177], v[198:201], v[100:103]
	v_mfma_f32_16x16x32_bf16 v[96:99], v[182:185], v[198:201], v[96:99]
	v_mfma_f32_16x16x32_bf16 v[84:87], v[174:177], v[206:209], v[84:87]
	v_mfma_f32_16x16x32_bf16 v[80:83], v[182:185], v[206:209], v[80:83]
	v_mfma_f32_16x16x32_bf16 v[68:71], v[174:177], v[214:217], v[68:71]
	v_mfma_f32_16x16x32_bf16 v[64:67], v[182:185], v[214:217], v[64:67]
	s_setprio 0
	s_barrier
	s_add_i32 s38, s61, s0
	v_lshl_add_u64 v[218:219], v[218:219], 0, s[18:19]
	s_mov_b32 m0, s38
	ds_read_b128 v[186:189], v153 offset:49152
	ds_read_b128 v[190:193], v153 offset:50176
	ds_read_b128 v[194:197], v153 offset:51200
	ds_read_b128 v[198:201], v153 offset:52224
	ds_read_b128 v[202:205], v153 offset:53248
	ds_read_b128 v[206:209], v153 offset:54272
	ds_read_b128 v[210:213], v153 offset:55296
	ds_read_b128 v[214:217], v153 offset:56320
	global_load_lds_dwordx4 v[218:219], off
	s_add_i32 m0, s38, 0x2000
	s_add_u32 s36, s36, 0x100080
	v_lshl_add_u64 v[218:219], v[220:221], 0, s[18:19]
	s_addc_u32 s37, s37, 0
	s_add_i32 s38, s62, s0
	global_load_lds_dwordx4 v[218:219], off
	v_lshl_add_u64 v[218:219], s[36:37], 0, v[130:131]
	s_mov_b32 m0, s38
	s_nop 0
	global_load_lds_dwordx4 v[218:219], off
	v_lshl_add_u64 v[218:219], s[36:37], 0, v[134:135]
	s_add_i32 m0, s38, 0x2000
	s_nop 0
	global_load_lds_dwordx4 v[218:219], off
	v_lshl_add_u64 v[218:219], v[222:223], 0, s[18:19]
	s_mov_b32 m0, s40
	s_nop 0
	global_load_lds_dwordx4 v[218:219], off
	v_lshl_add_u64 v[218:219], v[224:225], 0, s[18:19]
	s_mov_b32 m0, s41
	s_nop 0
	global_load_lds_dwordx4 v[218:219], off
	s_waitcnt vmcnt(8) lgkmcnt(0)
	s_barrier
	s_setprio 1
	v_mfma_f32_16x16x32_bf16 v[60:63], v[144:147], v[186:189], v[60:63]
	v_mfma_f32_16x16x32_bf16 v[56:59], v[162:165], v[186:189], v[56:59]
	v_mfma_f32_16x16x32_bf16 v[44:47], v[144:147], v[194:197], v[44:47]
	v_mfma_f32_16x16x32_bf16 v[40:43], v[162:165], v[194:197], v[40:43]
	v_mfma_f32_16x16x32_bf16 v[28:31], v[144:147], v[202:205], v[28:31]
	v_mfma_f32_16x16x32_bf16 v[24:27], v[162:165], v[202:205], v[24:27]
	v_mfma_f32_16x16x32_bf16 v[12:15], v[144:147], v[210:213], v[12:15]
	v_mfma_f32_16x16x32_bf16 v[8:11], v[162:165], v[210:213], v[8:11]
	v_mfma_f32_16x16x32_bf16 v[60:63], v[156:159], v[190:193], v[60:63]
	v_mfma_f32_16x16x32_bf16 v[56:59], v[166:169], v[190:193], v[56:59]
	v_mfma_f32_16x16x32_bf16 v[44:47], v[156:159], v[198:201], v[44:47]
	v_mfma_f32_16x16x32_bf16 v[40:43], v[166:169], v[198:201], v[40:43]
	v_mfma_f32_16x16x32_bf16 v[28:31], v[156:159], v[206:209], v[28:31]
	v_mfma_f32_16x16x32_bf16 v[24:27], v[166:169], v[206:209], v[24:27]
	v_mfma_f32_16x16x32_bf16 v[12:15], v[156:159], v[214:217], v[12:15]
	v_mfma_f32_16x16x32_bf16 v[8:11], v[166:169], v[214:217], v[8:11]
	v_mfma_f32_16x16x32_bf16 v[52:55], v[170:173], v[186:189], v[52:55]
	v_mfma_f32_16x16x32_bf16 v[48:51], v[178:181], v[186:189], v[48:51]
	v_mfma_f32_16x16x32_bf16 v[36:39], v[170:173], v[194:197], v[36:39]
	v_mfma_f32_16x16x32_bf16 v[32:35], v[178:181], v[194:197], v[32:35]
	v_mfma_f32_16x16x32_bf16 v[20:23], v[170:173], v[202:205], v[20:23]
	v_mfma_f32_16x16x32_bf16 v[16:19], v[178:181], v[202:205], v[16:19]
	v_mfma_f32_16x16x32_bf16 v[4:7], v[170:173], v[210:213], v[4:7]
	v_mfma_f32_16x16x32_bf16 v[0:3], v[178:181], v[210:213], v[0:3]
	v_mfma_f32_16x16x32_bf16 v[52:55], v[174:177], v[190:193], v[52:55]
	v_mfma_f32_16x16x32_bf16 v[48:51], v[182:185], v[190:193], v[48:51]
	v_mfma_f32_16x16x32_bf16 v[36:39], v[174:177], v[198:201], v[36:39]
	v_mfma_f32_16x16x32_bf16 v[32:35], v[182:185], v[198:201], v[32:35]
	v_mfma_f32_16x16x32_bf16 v[20:23], v[174:177], v[206:209], v[20:23]
	v_mfma_f32_16x16x32_bf16 v[16:19], v[182:185], v[206:209], v[16:19]
	v_mfma_f32_16x16x32_bf16 v[4:7], v[174:177], v[214:217], v[4:7]
	v_mfma_f32_16x16x32_bf16 v[0:3], v[182:185], v[214:217], v[0:3]
	s_setprio 0
	s_barrier
	s_add_i32 s60, s60, 2
	s_add_u32 s30, s30, 0x100
	s_addc_u32 s31, s31, 0
	s_add_u32 s56, s56, 0x100
	s_addc_u32 s57, s57, 0
	s_cmp_gt_u32 s60, 61
	s_cbranch_scc0 .LBB0_842
	s_and_b64 vcc, exec, s[22:23]
	s_cbranch_vccz .LBB0_845
	s_barrier
